# shifted priority levels: trailing group 3 / lead group 2 in the K-loop, lead keeps 2 through epilogue and next-tile prologue, trailing drops to 1 for its epilogue
# speedup vs baseline: 1.0010x; 1.0010x over previous
; #define PG8_STAGE(bufoff, gbase, voff) do { _Pragma("unroll") for (int _i = 0; _i < 2; ++_i) \
;         __builtin_amdgcn_global_load_lds((const __attribute__((address_space(1))) unsigned*)((const char*)(gbase) + (voff)[_i]), (LAS unsigned*)(lds + (bufoff) + ldsw + _i * 8192), 16, 0, 0); } while (0)
; #define PG8_WAIT_V(n) asm volatile("s_waitcnt vmcnt(" #n ")" ::: "memory")
; #define PG8_BAR __builtin_amdgcn_s_barrier()
; template <class Epi, class SchedT, bool ALIGN_EPI, bool SP2>
; __device__ __forceinline__ void gemm_phase(LAS unsigned char* lds, const int ldk, const int nt, const SchedT& S, const Epi& E) {
;     ...
;     for (int i = 0; i < 2; ++i) { int R, C; stage_rc(tid * 16 + i * 8192, R, C); const int Rb = 2 * (R & ~31) + perm32(R & 31);
;         voffA[i] = (unsigned)(R * K + C) * 2u; voffB[i] = (unsigned)(Rb * K + C) * 2u; }
;     const size_t kstep = (size_t)(BK * 2);
;     const size_t hstep = (size_t)HALF * K * 2;
;     const size_t hstepB = (size_t)32 * K * 2;
;     const unsigned ldsw = (unsigned)wid * 1024u;
;     const int aoff = lds_byte(wr * 64 + fr, fq * 8), boff = lds_byte(wc * 32 + fr, fq * 8);
;     ...
;     Unit cur, nxt; int ui = 0;
;     if (!S.next(0, cur)) return;
;     f32x4 acc[2][2][4][2];
; #pragma unroll
;     for (int a = 0; a < 2; ++a)
; #pragma unroll
;         for (int b = 0; b < 2; ++b)
; #pragma unroll
;             for (int m = 0; m < 4; ++m)
; #pragma unroll
;                 for (int n = 0; n < 2; ++n) acc[a][b][m][n] = (f32x4){0.f, 0.f, 0.f, 0.f};
;     bf16x8 At[4][2], B0[2][2], B1[2][2];
;     const char* cA; const char* cB; S.ptrs(cur, cA, cB);
;     if constexpr (SP2) {
;         PG8_STAGE(PG8_SB(0, 0), cB, voffB); PG8_STAGE(PG8_SB(0, 1), cB + hstepB, voffB); PG8_STAGE(PG8_SA(0, 0), cA, voffA); PG8_STAGE(PG8_SA(0, 1), cA + hstep, voffA);
;         if (wr == 1) PG8_BAR;
;         PG8_WAIT_V(2); PG8_BAR;
;         PG8_STAGE(PG8_SB(1, 0), cB + kstep, voffB); PG8_STAGE(PG8_SA(1, 0), cA + kstep, voffA); PG8_STAGE(PG8_SB(1, 1), cB + hstepB + kstep, voffB);
;         PG8_WAIT_V(6); PG8_BAR;
;     } else {
;         PG8_STAGE(PG8_SB(0, 0), cB, voffB); PG8_STAGE(PG8_SA(0, 0), cA, voffA); PG8_STAGE(PG8_SB(0, 1), cB + hstepB, voffB); PG8_STAGE(PG8_SA(0, 1), cA + hstep, voffA);
;         if (wr == 1) PG8_BAR;
.LBB0_112:
	s_mul_i32 s12, s16, 0x7500000
	v_writelane_b32 v163, s12, 36
	s_lshl_b32 s12, s16, 19
	s_mov_b32 s13, s23
	v_writelane_b32 v163, s12, 37
	s_mov_b32 s17, s23
	s_and_b64 vcc, exec, s[0:1]
	v_writelane_b32 v163, s13, 38
	v_writelane_b32 v163, s16, 39
	s_lshl_b64 s[0:1], s[16:17], 17
	s_nop 0
	v_writelane_b32 v163, s17, 40
	v_writelane_b32 v163, s0, 41
	s_nop 1
	v_writelane_b32 v163, s1, 42
	s_cbranch_vccnz .LBB0_358
	v_ashrrev_i32_e32 v3, 31, v0
	v_lshrrev_b32_e32 v3, 26, v3
	v_add_u32_e32 v3, v0, v3
	v_ashrrev_i32_e32 v10, 6, v3
	v_bfe_i32 v3, v0, 27, 1
	v_lshlrev_b32_e32 v2, 4, v0
	v_lshrrev_b32_e32 v3, 22, v3
	v_add_u32_e32 v3, v2, v3
	v_and_b32_e32 v3, 0xfffffc00, v3
	v_sub_u32_e32 v3, v2, v3
	v_lshrrev_b32_e32 v4, 4, v3
	v_bitop3_b32 v3, v4, v3, 32 bitop3:0x6c
	v_ashrrev_i32_e32 v5, 31, v3
	v_lshrrev_b32_e32 v5, 26, v5
	v_add_u32_e32 v5, v3, v5
	v_lshlrev_b32_e32 v4, 3, v10
	v_ashrrev_i32_e32 v11, 6, v5
	v_and_b32_e32 v5, 0xc0, v5
	v_and_b32_e32 v4, -16, v4
	v_sub_u32_e32 v3, v3, v5
	v_add_u32_e32 v4, v11, v4
	v_ashrrev_i16_sdwa v3, v244, sext(v3) dst_sel:DWORD dst_unused:UNUSED_PAD src0_sel:DWORD src1_sel:BYTE_0
	v_readlane_b32 s0, v163, 39
	v_lshlrev_b32_e32 v6, 5, v10
	v_bfe_i32 v12, v3, 0, 16
	v_lshlrev_b32_e32 v3, 1, v4
	v_lshrrev_b32_e32 v5, 2, v4
	s_mul_i32 s0, s0, 0x7500000
	v_and_b32_e32 v6, 32, v6
	v_and_b32_e32 v5, 4, v5
	v_and_b32_e32 v7, 3, v11
	v_and_b32_e32 v3, 0xfffd8, v3
	v_readlane_b32 s1, v163, 40
	s_add_u32 s0, s44, s0
	v_or3_b32 v3, v7, v5, v3
	v_add_lshl_u32 v5, v6, v12, 1
	v_add_u32_e32 v2, 0x2000, v2
	s_addc_u32 s1, s45, 0
	v_lshl_add_u32 v158, v3, 12, v5
	v_ashrrev_i32_e32 v3, 31, v2
	s_add_u32 s22, s0, 0x200000
	v_lshrrev_b32_e32 v3, 22, v3
	s_addc_u32 s84, s1, 0
	v_add_u32_e32 v3, v2, v3
	s_add_u32 s85, s44, 0xec00000
	v_ashrrev_i32_e32 v13, 10, v3
	s_addc_u32 s86, s45, 0
	s_ashr_i32 s0, s18, 6
	v_mul_i32_i24_e32 v3, 0x400, v13
	v_sub_u32_e32 v2, v2, v3
	s_ashr_i32 s94, s18, 8
	s_lshl_b32 s87, s0, 10
	v_lshrrev_b32_e32 v3, 4, v2
	s_cmp_eq_u32 s20, 0
	v_bitop3_b32 v2, v3, v2, 32 bitop3:0x6c
	s_cselect_b32 s12, s82, s51
	v_lshl_add_u32 v156, v4, 12, v5
	v_ashrrev_i32_e32 v4, 31, v2
	s_cselect_b32 s1, s86, s84
	s_cselect_b32 s17, s85, s22
	s_cselect_b32 s16, s51, s82
	s_cselect_b32 s19, s84, s86
	s_cselect_b32 s21, s22, s85
	s_ashr_i32 s13, s12, 31
	v_lshrrev_b32_e32 v4, 26, v4
	s_lshl_b64 s[12:13], s[12:13], 20
	v_add_u32_e32 v4, v2, v4
	s_add_u32 s12, s17, s12
	v_lshlrev_b32_e32 v3, 3, v13
	v_ashrrev_i32_e32 v14, 6, v4
	v_and_b32_e32 v4, 0xc0, v4
	s_addc_u32 s13, s1, s13
	s_ashr_i32 s17, s16, 31
	v_and_b32_e32 v3, -16, v3
	v_sub_u32_e32 v2, v2, v4
	s_lshl_b64 s[16:17], s[16:17], 20
	v_add_u32_e32 v3, v14, v3
	v_ashrrev_i16_sdwa v2, v244, sext(v2) dst_sel:DWORD dst_unused:UNUSED_PAD src0_sel:DWORD src1_sel:BYTE_0
	s_add_u32 s16, s21, s16
	v_lshlrev_b32_e32 v5, 5, v13
	v_bfe_i32 v15, v2, 0, 16
	v_lshlrev_b32_e32 v2, 1, v3
	v_lshrrev_b32_e32 v4, 2, v3
	s_addc_u32 s17, s19, s17
	s_add_i32 s88, s87, 0
	v_and_b32_e32 v5, 32, v5
	v_and_b32_e32 v4, 4, v4
	v_and_b32_e32 v6, 3, v14
	v_and_b32_e32 v2, 0xfffd8, v2
	s_add_i32 m0, s88, 0x10000
	v_or3_b32 v2, v6, v4, v2
	v_add_lshl_u32 v4, v5, v15, 1
	global_load_lds_dwordx4 v158, s[16:17]
	s_add_i32 m0, s88, 0x12000
	v_lshl_add_u32 v174, v2, 12, v4
	s_add_u32 s30, s16, 0x20000
	global_load_lds_dwordx4 v174, s[16:17]
	s_addc_u32 s31, s17, 0
	s_add_i32 m0, s88, 0x14000
	s_add_i32 s89, s88, 0x2000
	global_load_lds_dwordx4 v158, s[30:31]
	s_add_i32 m0, s88, 0x16000
	v_lshl_add_u32 v160, v3, 12, v4
	global_load_lds_dwordx4 v174, s[30:31]
	s_mov_b32 m0, s88
	s_add_u32 s30, s12, 0x80000
	global_load_lds_dwordx4 v156, s[12:13]
	s_mov_b32 m0, s89
	s_addc_u32 s31, s13, 0
	s_add_i32 s90, s88, 0x4000
	global_load_lds_dwordx4 v160, s[12:13]
	s_mov_b32 m0, s90
	s_add_i32 s91, s88, 0x6000
	global_load_lds_dwordx4 v156, s[30:31]
	s_mov_b32 m0, s91
	v_mov_b32_e32 v159, v1
	global_load_lds_dwordx4 v160, s[30:31]
	v_mov_b32_e32 v175, v1
	v_mov_b32_e32 v157, v1
	v_mov_b32_e32 v161, v1
	s_cmp_eq_u32 s94, 1
	v_lshl_add_u64 v[8:9], s[16:17], 0, v[158:159]
	v_lshl_add_u64 v[6:7], s[16:17], 0, v[174:175]
	v_lshl_add_u64 v[2:3], s[12:13], 0, v[156:157]
	s_cselect_b64 s[46:47], -1, 0
	s_cmp_lg_u32 s94, 1
	v_lshl_add_u64 v[4:5], s[12:13], 0, v[160:161]
	s_setprio 2
	s_cbranch_scc1 .LBB0_115
	s_barrier
	s_setprio 3

; #define PG8_STAGE(bufoff, gbase, voff) do { _Pragma("unroll") for (int _i = 0; _i < 2; ++_i) \
;         __builtin_amdgcn_global_load_lds((const __attribute__((address_space(1))) unsigned*)((const char*)(gbase) + (voff)[_i]), (LAS unsigned*)(lds + (bufoff) + ldsw + _i * 8192), 16, 0, 0); } while (0)
; #define PG8_LDA(dst, b, h) do { _Pragma("unroll") for (int m = 0; m < 4; ++m) _Pragma("unroll") for (int k = 0; k < 2; ++k) dst[m][k] = *(const LAS bf16x8*)(lds + PG8_SA(b, h) + aoff + m * 2048 + k * 1024); } while (0)
; #define PG8_LDB(dst, b, h) do { _Pragma("unroll") for (int n = 0; n < 2; ++n) _Pragma("unroll") for (int k = 0; k < 2; ++k) dst[n][k] = *(const LAS bf16x8*)(lds + PG8_SB(b, h) + boff + n * 2048 + k * 1024); } while (0)
; #define PG8_MMA(ai, bj, At, Bt) do { __builtin_amdgcn_s_setprio(1); _Pragma("unroll") for (int m = 0; m < 4; ++m) _Pragma("unroll") for (int n = 0; n < 2; ++n) _Pragma("unroll") for (int k = 0; k < 2; ++k) \
;         acc[ai][bj][m][n] = __builtin_amdgcn_mfma_f32_16x16x32_bf16(Bt[n][k], At[m][k], acc[ai][bj][m][n], 0, 0, 0); __builtin_amdgcn_s_setprio(0); } while (0)
; #define PG8_WAIT_V(n) asm volatile("s_waitcnt vmcnt(" #n ")" ::: "memory")
; #define PG8_WAIT_L(n) asm volatile("s_waitcnt lgkmcnt(" #n ")" ::: "memory")
; template <class Epi, class SchedT, bool ALIGN_EPI, bool SP2>
; __device__ __forceinline__ void gemm_phase(LAS unsigned char* lds, const int ldk, const int nt, const SchedT& S, const Epi& E) {
;     ...
;         for (int t = 0; t < nt; t += 2) {
;             const bool last = (t == nt - 2);
;             const char* a1 = cA + (size_t)(t + 1) * kstep;
;             const char* a2 = last ? nA : cA + (size_t)(t + 2) * kstep; const char* b2 = last ? nB : cB + (size_t)(t + 2) * kstep;
;             const char* a3 = a2 + kstep; const char* b3 = b2 + kstep;
;             if constexpr (SP2) {
;             PG8_LDB(B0, 0, 0); PG8_LDB(B1, 0, 1); PG8_SCHED; PG8_LDA(At, 0, 0); PG8_STAGE(PG8_SA(1, 1), a1 + hstep, voffA);
;             PG8_WAIT_V(8); PG8_WAIT_L(0); PG8_BAR; PG8_MMA(0, 0, At, B0); PG8_MMA(0, 1, At, B1); PG8_BAR; PG8_SCHED;
;             PG8_LDA(At, 0, 1); PG8_STAGE(PG8_SB(0, 0), b2, voffB); PG8_STAGE(PG8_SB(0, 1), b2 + hstepB, voffB); PG8_STAGE(PG8_SA(0, 0), a2, voffA);
;             PG8_WAIT_V(8); PG8_WAIT_L(0); PG8_BAR; PG8_MMA(1, 0, At, B0); PG8_MMA(1, 1, At, B1); PG8_BAR; PG8_SCHED;
.LBB0_123:
	s_add_u32 s12, s0, 0xfff80080
	s_addc_u32 s13, s1, -1
	s_add_i32 s34, 0, 0x10000
	s_cmp_eq_u32 s21, 28
	s_cselect_b32 s17, s61, s13
	s_cselect_b32 s16, s60, s12
	v_add_u32_e32 v0, s34, v212
	s_cselect_b32 s13, s31, s19
	s_cselect_b32 s12, s30, s18
	s_add_i32 s38, 0, 0x14000
	s_waitcnt lgkmcnt(0)
	ds_read_b128 v[132:135], v0
	ds_read_b128 v[136:139], v0 offset:1024
	ds_read_b128 v[140:143], v0 offset:2048
	ds_read_b128 v[144:147], v0 offset:3072
	v_add_u32_e32 v0, s38, v212
	ds_read_b128 v[148:151], v0
	ds_read_b128 v[152:155], v0 offset:1024
	ds_read_b128 v[184:187], v0 offset:2048
	ds_read_b128 v[188:191], v0 offset:3072
	v_lshl_add_u64 v[2:3], s[0:1], 0, v[180:181]
	s_add_i32 m0, s88, 0xc000
	ds_read_b128 v[192:195], v216
	ds_read_b128 v[196:199], v216 offset:1024
	ds_read_b128 v[200:203], v216 offset:2048
	ds_read_b128 v[204:207], v216 offset:3072
	ds_read_b128 v[218:221], v216 offset:4096
	ds_read_b128 v[222:225], v216 offset:5120
	ds_read_b128 v[226:229], v216 offset:6144
	ds_read_b128 v[230:233], v216 offset:7168
	global_load_lds_dwordx4 v[2:3], off
	v_lshl_add_u64 v[2:3], s[0:1], 0, v[182:183]
	s_add_i32 m0, s88, 0xe000
	s_nop 0
	global_load_lds_dwordx4 v[2:3], off
	s_waitcnt vmcnt(8)
	s_waitcnt lgkmcnt(0)
	s_barrier
	s_waitcnt lgkmcnt(0)
	v_mfma_f32_16x16x32_bf16 v[128:131], v[132:135], v[192:195], v[128:131]
	v_mfma_f32_16x16x32_bf16 v[124:127], v[140:143], v[192:195], v[124:127]
	v_mfma_f32_16x16x32_bf16 v[112:115], v[132:135], v[200:203], v[112:115]
	v_mfma_f32_16x16x32_bf16 v[108:111], v[140:143], v[200:203], v[108:111]
	v_mfma_f32_16x16x32_bf16 v[96:99], v[132:135], v[218:221], v[96:99]
	v_mfma_f32_16x16x32_bf16 v[92:95], v[140:143], v[218:221], v[92:95]
	v_mfma_f32_16x16x32_bf16 v[80:83], v[132:135], v[226:229], v[80:83]
	v_mfma_f32_16x16x32_bf16 v[76:79], v[140:143], v[226:229], v[76:79]
	v_mfma_f32_16x16x32_bf16 v[128:131], v[136:139], v[196:199], v[128:131]
	v_mfma_f32_16x16x32_bf16 v[124:127], v[144:147], v[196:199], v[124:127]
	v_mfma_f32_16x16x32_bf16 v[112:115], v[136:139], v[204:207], v[112:115]
	v_mfma_f32_16x16x32_bf16 v[108:111], v[144:147], v[204:207], v[108:111]
	v_mfma_f32_16x16x32_bf16 v[96:99], v[136:139], v[222:225], v[96:99]
	v_mfma_f32_16x16x32_bf16 v[92:95], v[144:147], v[222:225], v[92:95]
	v_mfma_f32_16x16x32_bf16 v[80:83], v[136:139], v[230:233], v[80:83]
	v_mfma_f32_16x16x32_bf16 v[76:79], v[144:147], v[230:233], v[76:79]
	v_mfma_f32_16x16x32_bf16 v[120:123], v[148:151], v[192:195], v[120:123]
	v_mfma_f32_16x16x32_bf16 v[116:119], v[184:187], v[192:195], v[116:119]
	v_mfma_f32_16x16x32_bf16 v[104:107], v[148:151], v[200:203], v[104:107]
	v_mfma_f32_16x16x32_bf16 v[100:103], v[184:187], v[200:203], v[100:103]
	v_mfma_f32_16x16x32_bf16 v[88:91], v[148:151], v[218:221], v[88:91]
	v_mfma_f32_16x16x32_bf16 v[84:87], v[184:187], v[218:221], v[84:87]
	v_mfma_f32_16x16x32_bf16 v[72:75], v[148:151], v[226:229], v[72:75]
	v_mfma_f32_16x16x32_bf16 v[68:71], v[184:187], v[226:229], v[68:71]
	v_mfma_f32_16x16x32_bf16 v[120:123], v[152:155], v[196:199], v[120:123]
	v_mfma_f32_16x16x32_bf16 v[116:119], v[188:191], v[196:199], v[116:119]
	v_mfma_f32_16x16x32_bf16 v[104:107], v[152:155], v[204:207], v[104:107]
	v_mfma_f32_16x16x32_bf16 v[100:103], v[188:191], v[204:207], v[100:103]
	v_mfma_f32_16x16x32_bf16 v[88:91], v[152:155], v[222:225], v[88:91]
	v_mfma_f32_16x16x32_bf16 v[84:87], v[188:191], v[222:225], v[84:87]
	v_mfma_f32_16x16x32_bf16 v[72:75], v[152:155], v[230:233], v[72:75]
	v_mfma_f32_16x16x32_bf16 v[68:71], v[188:191], v[230:233], v[68:71]
	s_barrier
	s_add_i32 s34, s34, s87
	v_lshl_add_u64 v[208:209], s[12:13], 0, v[158:159]
	s_mov_b32 m0, s34
	ds_read_b128 v[192:195], v216 offset:16384
	ds_read_b128 v[196:199], v216 offset:17408
	ds_read_b128 v[200:203], v216 offset:18432
	ds_read_b128 v[204:207], v216 offset:19456
	ds_read_b128 v[218:221], v216 offset:20480
	ds_read_b128 v[222:225], v216 offset:21504
	ds_read_b128 v[226:229], v216 offset:22528
	ds_read_b128 v[230:233], v216 offset:23552
	global_load_lds_dwordx4 v[208:209], off
	s_add_i32 m0, s34, 0x2000
	s_add_u32 s34, s12, 0x20000
	v_lshl_add_u64 v[234:235], s[12:13], 0, v[174:175]
	s_addc_u32 s35, s13, 0
	s_add_i32 s38, s38, s87
	global_load_lds_dwordx4 v[234:235], off
	v_lshl_add_u64 v[2:3], s[34:35], 0, v[158:159]
	s_mov_b32 m0, s38
	v_lshl_add_u64 v[236:237], s[16:17], 0, v[156:157]
	global_load_lds_dwordx4 v[2:3], off
	v_lshl_add_u64 v[2:3], s[34:35], 0, v[174:175]
	s_add_i32 m0, s38, 0x2000
	v_lshl_add_u64 v[238:239], s[16:17], 0, v[160:161]
	global_load_lds_dwordx4 v[2:3], off
	s_mov_b32 m0, s88
	s_nop 0
	global_load_lds_dwordx4 v[236:237], off
	s_mov_b32 m0, s89
	s_nop 0
	global_load_lds_dwordx4 v[238:239], off
	s_waitcnt vmcnt(8)
	s_waitcnt lgkmcnt(0)
	s_barrier
; #define PG8_STAGE(bufoff, gbase, voff) do { _Pragma("unroll") for (int _i = 0; _i < 2; ++_i) \
;         __builtin_amdgcn_global_load_lds((const __attribute__((address_space(1))) unsigned*)((const char*)(gbase) + (voff)[_i]), (LAS unsigned*)(lds + (bufoff) + ldsw + _i * 8192), 16, 0, 0); } while (0)
; #define PG8_LDA(dst, b, h) do { _Pragma("unroll") for (int m = 0; m < 4; ++m) _Pragma("unroll") for (int k = 0; k < 2; ++k) dst[m][k] = *(const LAS bf16x8*)(lds + PG8_SA(b, h) + aoff + m * 2048 + k * 1024); } while (0)
; #define PG8_LDB(dst, b, h) do { _Pragma("unroll") for (int n = 0; n < 2; ++n) _Pragma("unroll") for (int k = 0; k < 2; ++k) dst[n][k] = *(const LAS bf16x8*)(lds + PG8_SB(b, h) + boff + n * 2048 + k * 1024); } while (0)
; #define PG8_MMA(ai, bj, At, Bt) do { __builtin_amdgcn_s_setprio(1); _Pragma("unroll") for (int m = 0; m < 4; ++m) _Pragma("unroll") for (int n = 0; n < 2; ++n) _Pragma("unroll") for (int k = 0; k < 2; ++k) \
;         acc[ai][bj][m][n] = __builtin_amdgcn_mfma_f32_16x16x32_bf16(Bt[n][k], At[m][k], acc[ai][bj][m][n], 0, 0, 0); __builtin_amdgcn_s_setprio(0); } while (0)
; #define PG8_WAIT_V(n) asm volatile("s_waitcnt vmcnt(" #n ")" ::: "memory")
; #define PG8_WAIT_L(n) asm volatile("s_waitcnt lgkmcnt(" #n ")" ::: "memory")
; #define PG8_BAR __builtin_amdgcn_s_barrier()
; #define PG8_SCHED __builtin_amdgcn_sched_barrier(0)
; template <class Epi, class SchedT, bool ALIGN_EPI, bool SP2>
; __device__ __forceinline__ void gemm_phase(LAS unsigned char* lds, const int ldk, const int nt, const SchedT& S, const Epi& E) {
;     ...
;             PG8_WAIT_V(8); PG8_WAIT_L(0); PG8_BAR; PG8_MMA(0, 0, At, B0); PG8_MMA(0, 1, At, B1); PG8_BAR; PG8_SCHED;
;             PG8_LDA(At, 0, 1); PG8_STAGE(PG8_SB(0, 0), b2, voffB); PG8_STAGE(PG8_SB(0, 1), b2 + hstepB, voffB); PG8_STAGE(PG8_SA(0, 0), a2, voffA);
;             PG8_WAIT_V(8); PG8_WAIT_L(0); PG8_BAR; PG8_MMA(1, 0, At, B0); PG8_MMA(1, 1, At, B1); PG8_BAR; PG8_SCHED;
;             PG8_LDB(B0, 1, 0); PG8_LDB(B1, 1, 1); PG8_SCHED; PG8_LDA(At, 1, 0); PG8_STAGE(PG8_SA(0, 1), a2 + hstep, voffA);
;             PG8_WAIT_V(8); PG8_WAIT_L(0); PG8_BAR; PG8_MMA(0, 0, At, B0); PG8_MMA(0, 1, At, B1); PG8_BAR; PG8_SCHED;
	s_waitcnt lgkmcnt(0)
	v_mfma_f32_16x16x32_bf16 v[64:67], v[132:135], v[192:195], v[64:67]
	v_mfma_f32_16x16x32_bf16 v[60:63], v[140:143], v[192:195], v[60:63]
	v_mfma_f32_16x16x32_bf16 v[48:51], v[132:135], v[200:203], v[48:51]
	v_mfma_f32_16x16x32_bf16 v[44:47], v[140:143], v[200:203], v[44:47]
	v_mfma_f32_16x16x32_bf16 v[32:35], v[132:135], v[218:221], v[32:35]
	v_mfma_f32_16x16x32_bf16 v[28:31], v[140:143], v[218:221], v[28:31]
	v_mfma_f32_16x16x32_bf16 v[16:19], v[132:135], v[226:229], v[16:19]
	v_mfma_f32_16x16x32_bf16 v[12:15], v[140:143], v[226:229], v[12:15]
	v_mfma_f32_16x16x32_bf16 v[64:67], v[136:139], v[196:199], v[64:67]
	v_mfma_f32_16x16x32_bf16 v[60:63], v[144:147], v[196:199], v[60:63]
	v_mfma_f32_16x16x32_bf16 v[48:51], v[136:139], v[204:207], v[48:51]
	v_mfma_f32_16x16x32_bf16 v[44:47], v[144:147], v[204:207], v[44:47]
	v_mfma_f32_16x16x32_bf16 v[32:35], v[136:139], v[222:225], v[32:35]
	v_mfma_f32_16x16x32_bf16 v[28:31], v[144:147], v[222:225], v[28:31]
	v_mfma_f32_16x16x32_bf16 v[16:19], v[136:139], v[230:233], v[16:19]
	v_mfma_f32_16x16x32_bf16 v[12:15], v[144:147], v[230:233], v[12:15]
	v_mfma_f32_16x16x32_bf16 v[56:59], v[148:151], v[192:195], v[56:59]
	v_mfma_f32_16x16x32_bf16 v[52:55], v[184:187], v[192:195], v[52:55]
	v_mfma_f32_16x16x32_bf16 v[40:43], v[148:151], v[200:203], v[40:43]
	v_mfma_f32_16x16x32_bf16 v[36:39], v[184:187], v[200:203], v[36:39]
	v_mfma_f32_16x16x32_bf16 v[24:27], v[148:151], v[218:221], v[24:27]
	v_mfma_f32_16x16x32_bf16 v[20:23], v[184:187], v[218:221], v[20:23]
	v_mfma_f32_16x16x32_bf16 v[8:11], v[148:151], v[226:229], v[8:11]
	v_mfma_f32_16x16x32_bf16 v[2:5], v[184:187], v[226:229], v[4:7]
	v_mfma_f32_16x16x32_bf16 v[56:59], v[152:155], v[196:199], v[56:59]
	v_mfma_f32_16x16x32_bf16 v[52:55], v[188:191], v[196:199], v[52:55]
	v_mfma_f32_16x16x32_bf16 v[40:43], v[152:155], v[204:207], v[40:43]
	v_mfma_f32_16x16x32_bf16 v[36:39], v[188:191], v[204:207], v[36:39]
	v_mfma_f32_16x16x32_bf16 v[24:27], v[152:155], v[222:225], v[24:27]
	v_mfma_f32_16x16x32_bf16 v[20:23], v[188:191], v[222:225], v[20:23]
	v_mfma_f32_16x16x32_bf16 v[8:11], v[152:155], v[230:233], v[8:11]
	v_mfma_f32_16x16x32_bf16 v[2:5], v[188:191], v[230:233], v[2:5]
	s_barrier
	s_add_i32 s34, 0, 0x18000
	v_add_u32_e32 v0, s34, v212
	s_add_i32 s35, 0, 0x1c000
	ds_read_b128 v[132:135], v0
	ds_read_b128 v[136:139], v0 offset:1024
	ds_read_b128 v[140:143], v0 offset:2048
	ds_read_b128 v[144:147], v0 offset:3072
	v_add_u32_e32 v0, s35, v212
	ds_read_b128 v[148:151], v0
	ds_read_b128 v[152:155], v0 offset:1024
	ds_read_b128 v[184:187], v0 offset:2048
	ds_read_b128 v[188:191], v0 offset:3072
	s_add_u32 s16, s16, 0x80000
	s_addc_u32 s17, s17, 0
	s_mov_b32 m0, s90
	v_lshl_add_u64 v[6:7], s[16:17], 0, v[156:157]
	ds_read_b128 v[192:195], v216 offset:32768
	ds_read_b128 v[196:199], v216 offset:33792
	ds_read_b128 v[200:203], v216 offset:34816
	ds_read_b128 v[204:207], v216 offset:35840
	ds_read_b128 v[218:221], v216 offset:36864
	ds_read_b128 v[222:225], v216 offset:37888
	ds_read_b128 v[226:229], v216 offset:38912
	ds_read_b128 v[230:233], v216 offset:39936
	global_load_lds_dwordx4 v[6:7], off
	v_lshl_add_u64 v[6:7], s[16:17], 0, v[160:161]
	s_mov_b32 m0, s91
	s_nop 0
	global_load_lds_dwordx4 v[6:7], off
	s_waitcnt vmcnt(8)
	s_waitcnt lgkmcnt(0)
	s_barrier
	s_waitcnt lgkmcnt(0)
	v_mfma_f32_16x16x32_bf16 v[128:131], v[132:135], v[192:195], v[128:131]
	v_mfma_f32_16x16x32_bf16 v[124:127], v[140:143], v[192:195], v[124:127]
	v_mfma_f32_16x16x32_bf16 v[112:115], v[132:135], v[200:203], v[112:115]
	v_mfma_f32_16x16x32_bf16 v[108:111], v[140:143], v[200:203], v[108:111]
	v_mfma_f32_16x16x32_bf16 v[96:99], v[132:135], v[218:221], v[96:99]
	v_mfma_f32_16x16x32_bf16 v[92:95], v[140:143], v[218:221], v[92:95]
	v_mfma_f32_16x16x32_bf16 v[80:83], v[132:135], v[226:229], v[80:83]
	v_mfma_f32_16x16x32_bf16 v[76:79], v[140:143], v[226:229], v[76:79]
	v_mfma_f32_16x16x32_bf16 v[128:131], v[136:139], v[196:199], v[128:131]
	v_mfma_f32_16x16x32_bf16 v[124:127], v[144:147], v[196:199], v[124:127]
	v_mfma_f32_16x16x32_bf16 v[112:115], v[136:139], v[204:207], v[112:115]
	v_mfma_f32_16x16x32_bf16 v[108:111], v[144:147], v[204:207], v[108:111]
	v_mfma_f32_16x16x32_bf16 v[96:99], v[136:139], v[222:225], v[96:99]
	v_mfma_f32_16x16x32_bf16 v[92:95], v[144:147], v[222:225], v[92:95]
	v_mfma_f32_16x16x32_bf16 v[80:83], v[136:139], v[230:233], v[80:83]
	v_mfma_f32_16x16x32_bf16 v[76:79], v[144:147], v[230:233], v[76:79]
	v_mfma_f32_16x16x32_bf16 v[120:123], v[148:151], v[192:195], v[120:123]
	v_mfma_f32_16x16x32_bf16 v[116:119], v[184:187], v[192:195], v[116:119]
	v_mfma_f32_16x16x32_bf16 v[104:107], v[148:151], v[200:203], v[104:107]
	v_mfma_f32_16x16x32_bf16 v[100:103], v[184:187], v[200:203], v[100:103]
	v_mfma_f32_16x16x32_bf16 v[88:91], v[148:151], v[218:221], v[88:91]
	v_mfma_f32_16x16x32_bf16 v[84:87], v[184:187], v[218:221], v[84:87]
	v_mfma_f32_16x16x32_bf16 v[72:75], v[148:151], v[226:229], v[72:75]
	v_mfma_f32_16x16x32_bf16 v[68:71], v[184:187], v[226:229], v[68:71]
	v_mfma_f32_16x16x32_bf16 v[120:123], v[152:155], v[196:199], v[120:123]
	v_mfma_f32_16x16x32_bf16 v[116:119], v[188:191], v[196:199], v[116:119]
	v_mfma_f32_16x16x32_bf16 v[104:107], v[152:155], v[204:207], v[104:107]
	v_mfma_f32_16x16x32_bf16 v[100:103], v[188:191], v[204:207], v[100:103]
	v_mfma_f32_16x16x32_bf16 v[88:91], v[152:155], v[222:225], v[88:91]
	v_mfma_f32_16x16x32_bf16 v[84:87], v[188:191], v[222:225], v[84:87]
	v_mfma_f32_16x16x32_bf16 v[72:75], v[152:155], v[230:233], v[72:75]
	v_mfma_f32_16x16x32_bf16 v[68:71], v[188:191], v[230:233], v[68:71]
	s_barrier
; #define PG8_STAGE(bufoff, gbase, voff) do { _Pragma("unroll") for (int _i = 0; _i < 2; ++_i) \
;         __builtin_amdgcn_global_load_lds((const __attribute__((address_space(1))) unsigned*)((const char*)(gbase) + (voff)[_i]), (LAS unsigned*)(lds + (bufoff) + ldsw + _i * 8192), 16, 0, 0); } while (0)
; #define PG8_LDA(dst, b, h) do { _Pragma("unroll") for (int m = 0; m < 4; ++m) _Pragma("unroll") for (int k = 0; k < 2; ++k) dst[m][k] = *(const LAS bf16x8*)(lds + PG8_SA(b, h) + aoff + m * 2048 + k * 1024); } while (0)
; #define PG8_MMA(ai, bj, At, Bt) do { __builtin_amdgcn_s_setprio(1); _Pragma("unroll") for (int m = 0; m < 4; ++m) _Pragma("unroll") for (int n = 0; n < 2; ++n) _Pragma("unroll") for (int k = 0; k < 2; ++k) \
;         acc[ai][bj][m][n] = __builtin_amdgcn_mfma_f32_16x16x32_bf16(Bt[n][k], At[m][k], acc[ai][bj][m][n], 0, 0, 0); __builtin_amdgcn_s_setprio(0); } while (0)
; #define PG8_WAIT_V(n) asm volatile("s_waitcnt vmcnt(" #n ")" ::: "memory")
; #define PG8_WAIT_L(n) asm volatile("s_waitcnt lgkmcnt(" #n ")" ::: "memory")
; #define PG8_BAR __builtin_amdgcn_s_barrier()
; #define PG8_SCHED __builtin_amdgcn_sched_barrier(0)
; template <class Epi, class SchedT, bool ALIGN_EPI, bool SP2>
; __device__ __forceinline__ void gemm_phase(LAS unsigned char* lds, const int ldk, const int nt, const SchedT& S, const Epi& E) {
;     ...
;             PG8_LDA(At, 1, 1); PG8_STAGE(PG8_SB(1, 0), b3, voffB); PG8_STAGE(PG8_SB(1, 1), b3 + hstepB, voffB); PG8_STAGE(PG8_SA(1, 0), a3, voffA);
;             PG8_WAIT_V(8); PG8_WAIT_L(0); PG8_BAR; PG8_MMA(1, 0, At, B0); PG8_MMA(1, 1, At, B1); PG8_BAR; PG8_SCHED;
;     ...
;         if constexpr (ALIGN_EPI) { if (wr == 0) PG8_BAR; }
	s_add_i32 s16, s34, s87
	v_lshl_add_u64 v[6:7], v[208:209], 0, s[24:25]
	s_mov_b32 m0, s16
	ds_read_b128 v[192:195], v216 offset:49152
	ds_read_b128 v[196:199], v216 offset:50176
	ds_read_b128 v[200:203], v216 offset:51200
	ds_read_b128 v[204:207], v216 offset:52224
	ds_read_b128 v[218:221], v216 offset:53248
	ds_read_b128 v[222:225], v216 offset:54272
	ds_read_b128 v[226:229], v216 offset:55296
	ds_read_b128 v[230:233], v216 offset:56320
	global_load_lds_dwordx4 v[6:7], off
	s_add_i32 m0, s16, 0x2000
	s_add_u32 s12, s12, 0x20080
	v_lshl_add_u64 v[6:7], v[234:235], 0, s[24:25]
	s_addc_u32 s13, s13, 0
	s_add_i32 s16, s35, s87
	global_load_lds_dwordx4 v[6:7], off
	v_lshl_add_u64 v[6:7], s[12:13], 0, v[158:159]
	s_mov_b32 m0, s16
	s_nop 0
	global_load_lds_dwordx4 v[6:7], off
	v_lshl_add_u64 v[6:7], s[12:13], 0, v[174:175]
	s_add_i32 m0, s16, 0x2000
	s_nop 0
	global_load_lds_dwordx4 v[6:7], off
	v_lshl_add_u64 v[6:7], v[236:237], 0, s[24:25]
	s_mov_b32 m0, s92
	s_nop 0
	global_load_lds_dwordx4 v[6:7], off
	v_lshl_add_u64 v[6:7], v[238:239], 0, s[24:25]
	s_mov_b32 m0, s93
	s_nop 0
	global_load_lds_dwordx4 v[6:7], off
	s_waitcnt vmcnt(8)
	s_waitcnt lgkmcnt(0)
	s_barrier
	s_waitcnt lgkmcnt(0)
	v_mfma_f32_16x16x32_bf16 v[64:67], v[132:135], v[192:195], v[64:67]
	v_mfma_f32_16x16x32_bf16 v[60:63], v[140:143], v[192:195], v[60:63]
	v_mfma_f32_16x16x32_bf16 v[48:51], v[132:135], v[200:203], v[48:51]
	v_mfma_f32_16x16x32_bf16 v[44:47], v[140:143], v[200:203], v[44:47]
	v_mfma_f32_16x16x32_bf16 v[32:35], v[132:135], v[218:221], v[32:35]
	v_mfma_f32_16x16x32_bf16 v[28:31], v[140:143], v[218:221], v[28:31]
	v_mfma_f32_16x16x32_bf16 v[16:19], v[132:135], v[226:229], v[16:19]
	v_mfma_f32_16x16x32_bf16 v[12:15], v[140:143], v[226:229], v[12:15]
	v_mfma_f32_16x16x32_bf16 v[64:67], v[136:139], v[196:199], v[64:67]
	v_mfma_f32_16x16x32_bf16 v[60:63], v[144:147], v[196:199], v[60:63]
	v_mfma_f32_16x16x32_bf16 v[48:51], v[136:139], v[204:207], v[48:51]
	v_mfma_f32_16x16x32_bf16 v[44:47], v[144:147], v[204:207], v[44:47]
	v_mfma_f32_16x16x32_bf16 v[32:35], v[136:139], v[222:225], v[32:35]
	v_mfma_f32_16x16x32_bf16 v[28:31], v[144:147], v[222:225], v[28:31]
	v_mfma_f32_16x16x32_bf16 v[16:19], v[136:139], v[230:233], v[16:19]
	v_mfma_f32_16x16x32_bf16 v[12:15], v[144:147], v[230:233], v[12:15]
	v_mfma_f32_16x16x32_bf16 v[56:59], v[148:151], v[192:195], v[56:59]
	v_mfma_f32_16x16x32_bf16 v[52:55], v[184:187], v[192:195], v[52:55]
	v_mfma_f32_16x16x32_bf16 v[40:43], v[148:151], v[200:203], v[40:43]
	v_mfma_f32_16x16x32_bf16 v[36:39], v[184:187], v[200:203], v[36:39]
	v_mfma_f32_16x16x32_bf16 v[24:27], v[148:151], v[218:221], v[24:27]
	v_mfma_f32_16x16x32_bf16 v[20:23], v[184:187], v[218:221], v[20:23]
	v_mfma_f32_16x16x32_bf16 v[6:9], v[148:151], v[226:229], v[8:11]
	v_mfma_f32_16x16x32_bf16 v[2:5], v[184:187], v[226:229], v[2:5]
	v_mfma_f32_16x16x32_bf16 v[56:59], v[152:155], v[196:199], v[56:59]
	v_mfma_f32_16x16x32_bf16 v[52:55], v[188:191], v[196:199], v[52:55]
	v_mfma_f32_16x16x32_bf16 v[40:43], v[152:155], v[204:207], v[40:43]
	v_mfma_f32_16x16x32_bf16 v[36:39], v[188:191], v[204:207], v[36:39]
	v_mfma_f32_16x16x32_bf16 v[24:27], v[152:155], v[222:225], v[24:27]
	v_mfma_f32_16x16x32_bf16 v[20:23], v[188:191], v[222:225], v[20:23]
	v_mfma_f32_16x16x32_bf16 v[8:11], v[152:155], v[230:233], v[6:9]
	v_mfma_f32_16x16x32_bf16 v[4:7], v[188:191], v[230:233], v[2:5]
	s_barrier
	s_add_i32 s21, s21, 2
	s_add_u32 s0, s0, 0x100
	s_addc_u32 s1, s1, 0
	s_add_u32 s18, s18, 0x100
	s_addc_u32 s19, s19, 0
	s_cmp_gt_u32 s21, 29
	s_cbranch_scc0 .LBB0_123
	s_and_b64 vcc, exec, s[58:59]
	s_cbranch_vccnz .Lg0bar_p1
	s_setprio 1
	s_branch .LBB0_126
.Lg0bar_p1:
	s_barrier
	s_setprio 2

; #define PG8_BAR __builtin_amdgcn_s_barrier()
; template <class Epi, class SchedT, bool ALIGN_EPI, bool SP2>
; __device__ __forceinline__ void gemm_phase(LAS unsigned char* lds, const int ldk, const int nt, const SchedT& S, const Epi& E) {
;     ...
;         if (!has_next) break;
;         if (!(SchedT::kMode == 2 && cur.kind == 0)) {
; #pragma unroll
;         for (int a = 0; a < 2; ++a)
; #pragma unroll
;             for (int b = 0; b < 2; ++b)
; #pragma unroll
;                 for (int m = 0; m < 4; ++m)
; #pragma unroll
;                     for (int n = 0; n < 2; ++n) acc[a][b][m][n] = (f32x4){0.f, 0.f, 0.f, 0.f};
;         }
;         cur = nxt; cA = nA; cB = nB; ++ui;
;         if constexpr (ALIGN_EPI) { if (wr == 1) PG8_BAR; }
.LBB0_199:
.LBB0_203:
.LBB0_204:
.LBB0_206:
.LBB0_207:
.LBB0_210:
.LBB0_212:
.LBB0_213:
.LBB0_214:
.LBB0_216:
.LBB0_217:
.LBB0_218:
.LBB0_219:
.LBB0_220:
.LBB0_221:
.LBB0_222:
.LBB0_226:
.LBB0_227:
.LBB0_229:
.LBB0_230:
.LBB0_233:
.LBB0_235:
.LBB0_236:
.LBB0_237:
.LBB0_240:
.LBB0_241:
.LBB0_242:
.LBB0_243:
.LBB0_244:
.LBB0_245:
.LBB0_246:
.LBB0_247:
.LBB0_249:
.LBB0_252:
.LBB0_253:
.LBB0_254:
.LBB0_256:
.LBB0_259:
.LBB0_260:
.LBB0_261:
.LBB0_263:
.LBB0_266:
.LBB0_267:
.LBB0_268:
.LBB0_270:
.LBB0_273:
.LBB0_274:
.LBB0_275:
.LBB0_277:
.LBB0_280:
.LBB0_281:
.LBB0_282:
.LBB0_284:
.LBB0_287:
.LBB0_288:
.LBB0_289:
.LBB0_291:
.LBB0_294:
.LBB0_295:
.LBB0_296:
.LBB0_298:
.LBB0_301:
.LBB0_302:
.LBB0_303:
.LBB0_305:
.LBB0_308:
.LBB0_309:
.LBB0_310:
.LBB0_312:
.LBB0_315:
.LBB0_316:
.LBB0_317:
.LBB0_319:
.LBB0_322:
.LBB0_323:
.LBB0_324:
.LBB0_326:
.LBB0_329:
.LBB0_330:
.LBB0_331:
.LBB0_333:
.LBB0_336:
.LBB0_337:
.LBB0_338:
.LBB0_340:
.LBB0_343:
.LBB0_344:
.LBB0_345:
.LBB0_347:
.LBB0_350:
.LBB0_351:
.LBB0_352:
.LBB0_354:
	s_and_b64 vcc, exec, s[36:37]
	s_mov_b64 s[0:1], -1
	s_cbranch_vccnz .LBB0_117
	s_setprio 2
	s_andn2_b64 vcc, exec, s[46:47]
	s_cbranch_vccnz .LBB0_116
	s_barrier
	s_setprio 3
	s_branch .LBB0_116

; #define PG8_STAGE(bufoff, gbase, voff) do { _Pragma("unroll") for (int _i = 0; _i < 2; ++_i) \
;         __builtin_amdgcn_global_load_lds((const __attribute__((address_space(1))) unsigned*)((const char*)(gbase) + (voff)[_i]), (LAS unsigned*)(lds + (bufoff) + ldsw + _i * 8192), 16, 0, 0); } while (0)
; #define PG8_BAR __builtin_amdgcn_s_barrier()
; template <class Epi, class SchedT, bool ALIGN_EPI, bool SP2>
; __device__ __forceinline__ void gemm_phase(LAS unsigned char* lds, const int ldk, const int nt, const SchedT& S, const Epi& E) {
;     ...
;     for (int i = 0; i < 2; ++i) { int R, C; stage_rc(tid * 16 + i * 8192, R, C); const int Rb = 2 * (R & ~31) + perm32(R & 31);
;         voffA[i] = (unsigned)(R * K + C) * 2u; voffB[i] = (unsigned)(Rb * K + C) * 2u; }
;     const size_t kstep = (size_t)(BK * 2);
;     const size_t hstep = (size_t)HALF * K * 2;
;     const size_t hstepB = (size_t)32 * K * 2;
;     const unsigned ldsw = (unsigned)wid * 1024u;
;     const int aoff = lds_byte(wr * 64 + fr, fq * 8), boff = lds_byte(wc * 32 + fr, fq * 8);
;     ...
;     Unit cur, nxt; int ui = 0;
;     if (!S.next(0, cur)) return;
;     f32x4 acc[2][2][4][2];
; #pragma unroll
;     for (int a = 0; a < 2; ++a)
; #pragma unroll
;         for (int b = 0; b < 2; ++b)
; #pragma unroll
;             for (int m = 0; m < 4; ++m)
; #pragma unroll
;                 for (int n = 0; n < 2; ++n) acc[a][b][m][n] = (f32x4){0.f, 0.f, 0.f, 0.f};
;     bf16x8 At[4][2], B0[2][2], B1[2][2];
;     const char* cA; const char* cB; S.ptrs(cur, cA, cB);
;     if constexpr (SP2) {
;         PG8_STAGE(PG8_SB(0, 0), cB, voffB); PG8_STAGE(PG8_SB(0, 1), cB + hstepB, voffB); PG8_STAGE(PG8_SA(0, 0), cA, voffA); PG8_STAGE(PG8_SA(0, 1), cA + hstep, voffA);
;         if (wr == 1) PG8_BAR;
.LBB0_523:
	v_readlane_b32 s18, v163, 43
	v_readlane_b32 s19, v163, 44
	s_and_b64 vcc, exec, s[18:19]
	s_cbranch_vccnz .LBB0_607
	v_ashrrev_i32_e32 v3, 31, v0
	v_lshrrev_b32_e32 v3, 26, v3
	v_add_u32_e32 v3, v0, v3
	v_ashrrev_i32_e32 v10, 6, v3
	v_bfe_i32 v3, v0, 27, 1
	v_lshlrev_b32_e32 v2, 4, v0
	v_lshrrev_b32_e32 v3, 22, v3
	v_add_u32_e32 v3, v2, v3
	v_and_b32_e32 v3, 0xfffffc00, v3
	v_sub_u32_e32 v3, v2, v3
	v_lshrrev_b32_e32 v4, 4, v3
	v_bitop3_b32 v3, v4, v3, 32 bitop3:0x6c
	v_ashrrev_i32_e32 v5, 31, v3
	v_lshrrev_b32_e32 v5, 26, v5
	v_add_u32_e32 v5, v3, v5
	v_lshlrev_b32_e32 v4, 3, v10
	v_ashrrev_i32_e32 v11, 6, v5
	v_and_b32_e32 v5, 0xc0, v5
	v_and_b32_e32 v4, -16, v4
	v_sub_u32_e32 v3, v3, v5
	v_add_u32_e32 v4, v11, v4
	v_ashrrev_i16_sdwa v3, v244, sext(v3) dst_sel:DWORD dst_unused:UNUSED_PAD src0_sel:DWORD src1_sel:BYTE_0
	v_lshlrev_b32_e32 v6, 5, v10
	v_bfe_i32 v12, v3, 0, 16
	v_lshlrev_b32_e32 v3, 1, v4
	v_lshrrev_b32_e32 v5, 2, v4
	v_and_b32_e32 v6, 32, v6
	v_and_b32_e32 v5, 4, v5
	v_and_b32_e32 v7, 3, v11
	v_and_b32_e32 v3, 0xfffd8, v3
	v_or3_b32 v3, v7, v5, v3
	v_add_lshl_u32 v5, v6, v12, 1
	v_add_u32_e32 v2, 0x2000, v2
	v_lshl_add_u32 v134, v3, 12, v5
	v_ashrrev_i32_e32 v3, 31, v2
	v_lshrrev_b32_e32 v3, 22, v3
	v_add_u32_e32 v3, v2, v3
	v_ashrrev_i32_e32 v13, 10, v3
	v_readlane_b32 s18, v163, 39
	v_mul_i32_i24_e32 v3, 0x400, v13
	s_mul_i32 s13, s18, 0x7500000
	v_sub_u32_e32 v2, v2, v3
	s_add_u32 s13, s0, s13
	v_lshrrev_b32_e32 v3, 4, v2
	s_addc_u32 s17, s1, 0
	v_bitop3_b32 v2, v3, v2, 32 bitop3:0x6c
	s_add_u32 s21, s0, 0x1fc00000
	v_lshl_add_u32 v132, v4, 12, v5
	v_ashrrev_i32_e32 v4, 31, v2
	s_addc_u32 s22, s1, 0
	v_lshrrev_b32_e32 v4, 26, v4
	s_add_u32 s54, s13, 0x2600000
	v_add_u32_e32 v4, v2, v4
	v_readlane_b32 s19, v163, 40
	s_addc_u32 s55, s17, 0
	s_ashr_i32 s38, s20, 6
	v_lshlrev_b32_e32 v3, 3, v13
	v_ashrrev_i32_e32 v14, 6, v4
	v_and_b32_e32 v4, 0xc0, v4
	s_ashr_i32 s17, s16, 31
	s_ashr_i32 s13, s12, 31
	v_and_b32_e32 v3, -16, v3
	v_sub_u32_e32 v2, v2, v4
	s_ashr_i32 s39, s20, 8
	s_lshl_b32 s56, s38, 10
	s_lshl_b64 s[18:19], s[16:17], 20
	s_lshl_b64 s[30:31], s[12:13], 20
	v_add_u32_e32 v3, v14, v3
	v_ashrrev_i16_sdwa v2, v244, sext(v2) dst_sel:DWORD dst_unused:UNUSED_PAD src0_sel:DWORD src1_sel:BYTE_0
	s_add_u32 s36, s54, s30
	v_lshlrev_b32_e32 v5, 5, v13
	v_bfe_i32 v15, v2, 0, 16
	v_lshlrev_b32_e32 v2, 1, v3
	v_lshrrev_b32_e32 v4, 2, v3
	s_addc_u32 s37, s55, s31
	s_add_i32 s57, s56, 0
	v_and_b32_e32 v5, 32, v5
	v_and_b32_e32 v4, 4, v4
	v_and_b32_e32 v6, 3, v14
	v_and_b32_e32 v2, 0xfffd8, v2
	s_add_i32 m0, s57, 0x10000
	v_or3_b32 v2, v6, v4, v2
	v_add_lshl_u32 v4, v5, v15, 1
	global_load_lds_dwordx4 v134, s[36:37]
	s_add_i32 m0, s57, 0x12000
	v_lshl_add_u32 v138, v2, 12, v4
	s_add_u32 s30, s36, 0x20000
	global_load_lds_dwordx4 v138, s[36:37]
	s_addc_u32 s31, s37, 0
	s_add_i32 m0, s57, 0x14000
	v_lshl_add_u32 v136, v3, 12, v4
	global_load_lds_dwordx4 v134, s[30:31]
	s_add_i32 m0, s57, 0x16000
	s_add_u32 s34, s21, s18
	s_addc_u32 s35, s22, s19
	s_add_i32 s58, s57, 0x2000
	global_load_lds_dwordx4 v138, s[30:31]
	s_mov_b32 m0, s57
	s_add_u32 s18, s34, 0x80000
	global_load_lds_dwordx4 v132, s[34:35]
	s_mov_b32 m0, s58
	s_addc_u32 s19, s35, 0
	s_add_i32 s59, s57, 0x4000
	global_load_lds_dwordx4 v136, s[34:35]
	s_mov_b32 m0, s59
	s_add_i32 s60, s57, 0x6000
	global_load_lds_dwordx4 v132, s[18:19]
	s_mov_b32 m0, s60
	v_mov_b32_e32 v135, v1
	global_load_lds_dwordx4 v136, s[18:19]
	v_mov_b32_e32 v139, v1
	v_mov_b32_e32 v133, v1
	v_mov_b32_e32 v137, v1
	s_cmp_eq_u32 s39, 1
	v_lshl_add_u64 v[8:9], s[36:37], 0, v[134:135]
	v_lshl_add_u64 v[6:7], s[36:37], 0, v[138:139]
	v_lshl_add_u64 v[2:3], s[34:35], 0, v[132:133]
	s_cselect_b64 s[18:19], -1, 0
	s_cmp_lg_u32 s39, 1
	v_lshl_add_u64 v[4:5], s[34:35], 0, v[136:137]
	s_setprio 2
	s_cbranch_scc1 .LBB0_526
	s_barrier
	s_setprio 3

; #define PG8_BAR __builtin_amdgcn_s_barrier()
; template <class Epi, class SchedT, bool ALIGN_EPI, bool SP2>
; __device__ __forceinline__ void gemm_phase(LAS unsigned char* lds, const int ldk, const int nt, const SchedT& S, const Epi& E) {
;     ...
;         if (!has_next) break;
;         if (!(SchedT::kMode == 2 && cur.kind == 0)) {
; #pragma unroll
;         for (int a = 0; a < 2; ++a)
; #pragma unroll
;             for (int b = 0; b < 2; ++b)
; #pragma unroll
;                 for (int m = 0; m < 4; ++m)
; #pragma unroll
;                     for (int n = 0; n < 2; ++n) acc[a][b][m][n] = (f32x4){0.f, 0.f, 0.f, 0.f};
;         }
;         cur = nxt; cA = nA; cB = nB; ++ui;
;         if constexpr (ALIGN_EPI) { if (wr == 1) PG8_BAR; }
.LBB0_588:
	s_setprio 2
	s_andn2_b64 vcc, exec, s[18:19]
	s_cbranch_vccnz .LBB0_527
	s_barrier
	s_setprio 3
	s_branch .LBB0_527

; #define PG8_STAGE(bufoff, gbase, voff) do { _Pragma("unroll") for (int _i = 0; _i < 2; ++_i) \
;         __builtin_amdgcn_global_load_lds((const __attribute__((address_space(1))) unsigned*)((const char*)(gbase) + (voff)[_i]), (LAS unsigned*)(lds + (bufoff) + ldsw + _i * 8192), 16, 0, 0); } while (0)
; #define PG8_BAR __builtin_amdgcn_s_barrier()
; template <class Epi, class SchedT, bool ALIGN_EPI, bool SP2>
; __device__ __forceinline__ void gemm_phase(LAS unsigned char* lds, const int ldk, const int nt, const SchedT& S, const Epi& E) {
;     ...
;     for (int i = 0; i < 2; ++i) { int R, C; stage_rc(tid * 16 + i * 8192, R, C); const int Rb = 2 * (R & ~31) + perm32(R & 31);
;         voffA[i] = (unsigned)(R * K + C) * 2u; voffB[i] = (unsigned)(Rb * K + C) * 2u; }
;     const size_t kstep = (size_t)(BK * 2);
;     const size_t hstep = (size_t)HALF * K * 2;
;     const size_t hstepB = (size_t)32 * K * 2;
;     const unsigned ldsw = (unsigned)wid * 1024u;
;     const int aoff = lds_byte(wr * 64 + fr, fq * 8), boff = lds_byte(wc * 32 + fr, fq * 8);
;     ...
;     Unit cur, nxt; int ui = 0;
;     if (!S.next(0, cur)) return;
;     f32x4 acc[2][2][4][2];
; #pragma unroll
;     for (int a = 0; a < 2; ++a)
; #pragma unroll
;         for (int b = 0; b < 2; ++b)
; #pragma unroll
;             for (int m = 0; m < 4; ++m)
; #pragma unroll
;                 for (int n = 0; n < 2; ++n) acc[a][b][m][n] = (f32x4){0.f, 0.f, 0.f, 0.f};
;     bf16x8 At[4][2], B0[2][2], B1[2][2];
;     const char* cA; const char* cB; S.ptrs(cur, cA, cB);
;     if constexpr (SP2) {
;         PG8_STAGE(PG8_SB(0, 0), cB, voffB); PG8_STAGE(PG8_SB(0, 1), cB + hstepB, voffB); PG8_STAGE(PG8_SA(0, 0), cA, voffA); PG8_STAGE(PG8_SA(0, 1), cA + hstep, voffA);
;         if (wr == 1) PG8_BAR;
.LBB0_657:
	v_readlane_b32 s18, v163, 37
	v_readlane_b32 s19, v163, 38
	s_or_b32 s30, s18, 0x40000
	v_readlane_b32 s18, v163, 43
	v_readlane_b32 s19, v163, 44
	s_and_b64 vcc, exec, s[18:19]
	s_mov_b32 s31, s23
	s_cbranch_vccnz .LBB0_691
	v_ashrrev_i32_e32 v0, 31, v16
	v_lshrrev_b32_e32 v0, 26, v0
	v_add_u32_e32 v0, v16, v0
	v_ashrrev_i32_e32 v10, 6, v0
	v_bfe_i32 v0, v16, 27, 1
	v_lshlrev_b32_e32 v2, 4, v16
	v_lshrrev_b32_e32 v0, 22, v0
	v_add_u32_e32 v0, v2, v0
	v_and_b32_e32 v0, 0xfffffc00, v0
	v_sub_u32_e32 v0, v2, v0
	v_lshrrev_b32_e32 v3, 4, v0
	v_bitop3_b32 v0, v3, v0, 32 bitop3:0x6c
	v_ashrrev_i32_e32 v4, 31, v0
	v_lshrrev_b32_e32 v4, 26, v4
	v_add_u32_e32 v4, v0, v4
	v_lshlrev_b32_e32 v3, 3, v10
	v_ashrrev_i32_e32 v11, 6, v4
	v_and_b32_e32 v4, 0xc0, v4
	v_and_b32_e32 v3, -16, v3
	v_sub_u32_e32 v0, v0, v4
	v_add_u32_e32 v3, v11, v3
	v_ashrrev_i16_sdwa v0, v244, sext(v0) dst_sel:DWORD dst_unused:UNUSED_PAD src0_sel:DWORD src1_sel:BYTE_0
	v_lshlrev_b32_e32 v5, 5, v10
	v_bfe_i32 v12, v0, 0, 16
	v_lshlrev_b32_e32 v0, 1, v3
	v_lshrrev_b32_e32 v4, 2, v3
	v_and_b32_e32 v5, 32, v5
	v_and_b32_e32 v4, 4, v4
	v_and_b32_e32 v6, 3, v11
	v_and_b32_e32 v0, 0xfffd8, v0
	v_or3_b32 v0, v6, v4, v0
	v_add_lshl_u32 v4, v5, v12, 1
	v_add_u32_e32 v2, 0x2000, v2
	v_lshl_add_u32 v130, v3, 12, v4
	v_ashrrev_i32_e32 v3, 31, v2
	v_lshrrev_b32_e32 v3, 22, v3
	v_add_u32_e32 v3, v2, v3
	v_ashrrev_i32_e32 v13, 10, v3
	v_readlane_b32 s18, v163, 39
	v_mul_i32_i24_e32 v3, 0x400, v13
	s_mul_i32 s13, s18, 0x7500000
	v_sub_u32_e32 v2, v2, v3
	s_add_u32 s13, s0, s13
	v_lshrrev_b32_e32 v3, 4, v2
	s_addc_u32 s17, s1, 0
	v_bitop3_b32 v2, v3, v2, 32 bitop3:0x6c
	s_add_u32 s21, s0, 0x25c00000
	v_lshl_add_u32 v0, v0, 12, v4
	v_ashrrev_i32_e32 v4, 31, v2
	s_addc_u32 s58, s1, 0
	v_lshrrev_b32_e32 v4, 26, v4
	s_add_u32 s59, s13, 0x2e00000
	v_add_u32_e32 v4, v2, v4
	v_readlane_b32 s19, v163, 40
	s_addc_u32 s60, s17, 0
	s_ashr_i32 s22, s20, 6
	v_lshlrev_b32_e32 v3, 3, v13
	v_ashrrev_i32_e32 v14, 6, v4
	v_and_b32_e32 v4, 0xc0, v4
	s_ashr_i32 s17, s16, 31
	s_ashr_i32 s13, s12, 31
	v_and_b32_e32 v3, -16, v3
	v_sub_u32_e32 v2, v2, v4
	s_ashr_i32 s38, s20, 8
	s_lshl_b32 s61, s22, 10
	s_lshl_b64 s[18:19], s[16:17], 20
	s_lshl_b64 s[34:35], s[12:13], 20
	v_add_u32_e32 v3, v14, v3
	v_ashrrev_i16_sdwa v2, v244, sext(v2) dst_sel:DWORD dst_unused:UNUSED_PAD src0_sel:DWORD src1_sel:BYTE_0
	s_add_u32 s36, s59, s34
	v_lshlrev_b32_e32 v5, 5, v13
	v_bfe_i32 v15, v2, 0, 16
	v_lshlrev_b32_e32 v2, 1, v3
	v_lshrrev_b32_e32 v4, 2, v3
	s_addc_u32 s37, s60, s35
	s_add_i32 s17, s61, 0
	v_and_b32_e32 v5, 32, v5
	v_and_b32_e32 v4, 4, v4
	v_and_b32_e32 v6, 3, v14
	v_and_b32_e32 v2, 0xfffd8, v2
	s_add_i32 m0, s17, 0x10000
	v_or3_b32 v2, v6, v4, v2
	v_add_lshl_u32 v4, v5, v15, 1
	global_load_lds_dwordx4 v0, s[36:37]
	s_add_i32 m0, s17, 0x12000
	v_lshl_add_u32 v134, v2, 12, v4
	s_add_u32 s34, s36, 0x20000
	global_load_lds_dwordx4 v134, s[36:37]
	s_addc_u32 s35, s37, 0
	s_add_i32 m0, s17, 0x14000
	v_lshl_add_u32 v132, v3, 12, v4
	global_load_lds_dwordx4 v0, s[34:35]
	s_add_i32 m0, s17, 0x16000
	v_mov_b32_e32 v135, v1
	global_load_lds_dwordx4 v134, s[34:35]
	s_add_u32 s34, s21, s18
	s_addc_u32 s35, s58, s19
	s_add_i32 s62, s17, 0x2000
	s_mov_b32 m0, s17
	s_add_u32 s18, s34, 0x80000
	global_load_lds_dwordx4 v130, s[34:35]
	s_mov_b32 m0, s62
	s_addc_u32 s19, s35, 0
	s_add_i32 s63, s17, 0x4000
	global_load_lds_dwordx4 v132, s[34:35]
	s_mov_b32 m0, s63
	s_add_i32 s81, s17, 0x6000
	global_load_lds_dwordx4 v130, s[18:19]
	s_mov_b32 m0, s81
	v_mov_b32_e32 v131, v1
	global_load_lds_dwordx4 v132, s[18:19]
	v_mov_b32_e32 v133, v1
	s_cmp_eq_u32 s38, 1
	v_lshl_add_u64 v[8:9], s[36:37], 0, v[0:1]
	v_lshl_add_u64 v[6:7], s[36:37], 0, v[134:135]
	v_lshl_add_u64 v[2:3], s[34:35], 0, v[130:131]
	s_cselect_b64 s[18:19], -1, 0
	s_cmp_lg_u32 s38, 1
	v_lshl_add_u64 v[4:5], s[34:35], 0, v[132:133]
	s_setprio 2
	s_cbranch_scc1 .LBB0_660
	s_barrier
	s_setprio 3

; __device__ __forceinline__ float bf_lo(unsigned w) { return __uint_as_float(w << 16); }
; __device__ __forceinline__ float bf_hi(unsigned w) { return __uint_as_float(w & 0xffff0000u); }
; __device__ __forceinline__ u32x4 pack8(f32x4 a, f32x4 b) { u32x4 w; w.x = cvt_pk_bf16(a[0], a[1]); w.y = cvt_pk_bf16(a[2], a[3]); w.z = cvt_pk_bf16(b[0], b[1]); w.w = cvt_pk_bf16(b[2], b[3]); return w; }
;     __device__ __forceinline__ void operator()(f32x4 (&acc)[2][2][4][2], const Unit& u, int wr, int wc, int fr, int fq) const {
;     ...
;         for (int ai = 0; ai < 2; ++ai)
; #pragma unroll
;             for (int m = 0; m < 4; ++m) {
;                 const int row = row0 + ai * HALF + m * 16; float sq = 0.f;
; #pragma unroll
;                 for (int bj = 0; bj < 2; ++bj) {
;                     const size_t off = (size_t)row * D + col0 + bj * 32;
;                     const u32x4 xw = *(const u32x4*)(xin + off);
;                     const f32x4 v0 = acc[ai][bj][m][0] + (f32x4){bf_lo(xw.x), bf_hi(xw.x), bf_lo(xw.y), bf_hi(xw.y)}, v1 = acc[ai][bj][m][1] + (f32x4){bf_lo(xw.z), bf_hi(xw.z), bf_lo(xw.w), bf_hi(xw.w)};
;                     *(u32x4*)(xb + off) = pack8(v0, v1);
;                     sq += (v0[0] * v0[0] + v0[1] * v0[1]) + (v0[2] * v0[2] + v0[3] * v0[3]) + (v1[0] * v1[0] + v1[1] * v1[1]) + (v1[2] * v1[2] + v1[3] * v1[3]);
;                 }
.LBB0_671:
	s_waitcnt vmcnt(15)
	v_lshlrev_b32_e32 v246, 16, v174
	v_and_b32_e32 v247, 0xffff0000, v174
	v_lshlrev_b32_e32 v248, 16, v175
	v_and_b32_e32 v249, 0xffff0000, v175
	v_pk_add_f32 v[126:127], v[126:127], v[246:247]
	v_pk_add_f32 v[128:129], v[128:129], v[248:249]
	v_lshlrev_b32_e32 v246, 16, v176
	v_and_b32_e32 v247, 0xffff0000, v176
	v_lshlrev_b32_e32 v248, 16, v177
	v_and_b32_e32 v249, 0xffff0000, v177
	v_pk_add_f32 v[122:123], v[122:123], v[246:247]
	v_pk_add_f32 v[124:125], v[124:125], v[248:249]
	v_cvt_pk_bf16_f32 v174, v126, v127
	v_cvt_pk_bf16_f32 v175, v128, v129
	v_cvt_pk_bf16_f32 v176, v122, v123
	v_cvt_pk_bf16_f32 v177, v124, v125
	global_store_dwordx4 v150, v[174:177], s[44:45]
	v_pk_mul_f32 v[250:251], v[126:127], v[126:127]
	v_pk_fma_f32 v[250:251], v[128:129], v[128:129], v[250:251]
	v_pk_fma_f32 v[250:251], v[122:123], v[122:123], v[250:251]
	v_pk_fma_f32 v[250:251], v[124:125], v[124:125], v[250:251]
	s_waitcnt vmcnt(15)
	v_lshlrev_b32_e32 v246, 16, v178
	v_and_b32_e32 v247, 0xffff0000, v178
	v_lshlrev_b32_e32 v248, 16, v179
	v_and_b32_e32 v249, 0xffff0000, v179
	v_pk_add_f32 v[118:119], v[118:119], v[246:247]
	v_pk_add_f32 v[120:121], v[120:121], v[248:249]
	v_lshlrev_b32_e32 v246, 16, v180
	v_and_b32_e32 v247, 0xffff0000, v180
	v_lshlrev_b32_e32 v248, 16, v181
	v_and_b32_e32 v249, 0xffff0000, v181
	v_pk_add_f32 v[114:115], v[114:115], v[246:247]
	v_pk_add_f32 v[116:117], v[116:117], v[248:249]
	v_cvt_pk_bf16_f32 v178, v118, v119
	v_cvt_pk_bf16_f32 v179, v120, v121
	v_cvt_pk_bf16_f32 v180, v114, v115
	v_cvt_pk_bf16_f32 v181, v116, v117
	global_store_dwordx4 v150, v[178:181], s[44:45] offset:64
	v_pk_fma_f32 v[250:251], v[118:119], v[118:119], v[250:251]
	v_pk_fma_f32 v[250:251], v[120:121], v[120:121], v[250:251]
	v_pk_fma_f32 v[250:251], v[114:115], v[114:115], v[250:251]
	v_pk_fma_f32 v[250:251], v[116:117], v[116:117], v[250:251]
	v_add_f32_e32 v140, v250, v251
	s_waitcnt vmcnt(15)
	v_lshlrev_b32_e32 v246, 16, v182
	v_and_b32_e32 v247, 0xffff0000, v182
	v_lshlrev_b32_e32 v248, 16, v183
	v_and_b32_e32 v249, 0xffff0000, v183
	v_pk_add_f32 v[110:111], v[110:111], v[246:247]
	v_pk_add_f32 v[112:113], v[112:113], v[248:249]
	v_lshlrev_b32_e32 v246, 16, v184
	v_and_b32_e32 v247, 0xffff0000, v184
	v_lshlrev_b32_e32 v248, 16, v185
	v_and_b32_e32 v249, 0xffff0000, v185
	v_pk_add_f32 v[106:107], v[106:107], v[246:247]
	v_pk_add_f32 v[108:109], v[108:109], v[248:249]
	v_cvt_pk_bf16_f32 v182, v110, v111
	v_cvt_pk_bf16_f32 v183, v112, v113
	v_cvt_pk_bf16_f32 v184, v106, v107
	v_cvt_pk_bf16_f32 v185, v108, v109
	global_store_dwordx4 v151, v[182:185], s[44:45]
	v_pk_mul_f32 v[250:251], v[110:111], v[110:111]
	v_pk_fma_f32 v[250:251], v[112:113], v[112:113], v[250:251]
	v_pk_fma_f32 v[250:251], v[106:107], v[106:107], v[250:251]
	v_pk_fma_f32 v[250:251], v[108:109], v[108:109], v[250:251]
	s_waitcnt vmcnt(15)
	v_lshlrev_b32_e32 v246, 16, v186
	v_and_b32_e32 v247, 0xffff0000, v186
	v_lshlrev_b32_e32 v248, 16, v187
	v_and_b32_e32 v249, 0xffff0000, v187
	v_pk_add_f32 v[102:103], v[102:103], v[246:247]
	v_pk_add_f32 v[104:105], v[104:105], v[248:249]
	v_lshlrev_b32_e32 v246, 16, v188
	v_and_b32_e32 v247, 0xffff0000, v188
	v_lshlrev_b32_e32 v248, 16, v189
	v_and_b32_e32 v249, 0xffff0000, v189
	v_pk_add_f32 v[98:99], v[98:99], v[246:247]
	v_pk_add_f32 v[100:101], v[100:101], v[248:249]
	v_cvt_pk_bf16_f32 v186, v102, v103
	v_cvt_pk_bf16_f32 v187, v104, v105
	v_cvt_pk_bf16_f32 v188, v98, v99
	v_cvt_pk_bf16_f32 v189, v100, v101
	global_store_dwordx4 v151, v[186:189], s[44:45] offset:64
	v_pk_fma_f32 v[250:251], v[102:103], v[102:103], v[250:251]
	v_pk_fma_f32 v[250:251], v[104:105], v[104:105], v[250:251]
	v_pk_fma_f32 v[250:251], v[98:99], v[98:99], v[250:251]
	v_pk_fma_f32 v[250:251], v[100:101], v[100:101], v[250:251]
	v_add_f32_e32 v141, v250, v251
	s_waitcnt vmcnt(15)
	v_lshlrev_b32_e32 v246, 16, v190
	v_and_b32_e32 v247, 0xffff0000, v190
	v_lshlrev_b32_e32 v248, 16, v191
	v_and_b32_e32 v249, 0xffff0000, v191
	v_pk_add_f32 v[94:95], v[94:95], v[246:247]
	v_pk_add_f32 v[96:97], v[96:97], v[248:249]
	v_lshlrev_b32_e32 v246, 16, v192
	v_and_b32_e32 v247, 0xffff0000, v192
	v_lshlrev_b32_e32 v248, 16, v193
	v_and_b32_e32 v249, 0xffff0000, v193
	v_pk_add_f32 v[90:91], v[90:91], v[246:247]
	v_pk_add_f32 v[92:93], v[92:93], v[248:249]
	v_cvt_pk_bf16_f32 v190, v94, v95
	v_cvt_pk_bf16_f32 v191, v96, v97
	v_cvt_pk_bf16_f32 v192, v90, v91
	v_cvt_pk_bf16_f32 v193, v92, v93
	global_store_dwordx4 v152, v[190:193], s[44:45]
	v_pk_mul_f32 v[250:251], v[94:95], v[94:95]
	v_pk_fma_f32 v[250:251], v[96:97], v[96:97], v[250:251]
	v_pk_fma_f32 v[250:251], v[90:91], v[90:91], v[250:251]
	v_pk_fma_f32 v[250:251], v[92:93], v[92:93], v[250:251]
	s_waitcnt vmcnt(15)
	v_lshlrev_b32_e32 v246, 16, v194
	v_and_b32_e32 v247, 0xffff0000, v194
	v_lshlrev_b32_e32 v248, 16, v195
	v_and_b32_e32 v249, 0xffff0000, v195
	v_pk_add_f32 v[86:87], v[86:87], v[246:247]
	v_pk_add_f32 v[88:89], v[88:89], v[248:249]
	v_lshlrev_b32_e32 v246, 16, v196
	v_and_b32_e32 v247, 0xffff0000, v196
	v_lshlrev_b32_e32 v248, 16, v197
	v_and_b32_e32 v249, 0xffff0000, v197
	v_pk_add_f32 v[82:83], v[82:83], v[246:247]
	v_pk_add_f32 v[84:85], v[84:85], v[248:249]
	v_cvt_pk_bf16_f32 v194, v86, v87
	v_cvt_pk_bf16_f32 v195, v88, v89
	v_cvt_pk_bf16_f32 v196, v82, v83
	v_cvt_pk_bf16_f32 v197, v84, v85
	global_store_dwordx4 v152, v[194:197], s[44:45] offset:64
	v_pk_fma_f32 v[250:251], v[86:87], v[86:87], v[250:251]
	v_pk_fma_f32 v[250:251], v[88:89], v[88:89], v[250:251]
	v_pk_fma_f32 v[250:251], v[82:83], v[82:83], v[250:251]
	v_pk_fma_f32 v[250:251], v[84:85], v[84:85], v[250:251]
	v_add_f32_e32 v142, v250, v251
	s_waitcnt vmcnt(15)
; __device__ __forceinline__ float bf_lo(unsigned w) { return __uint_as_float(w << 16); }
; __device__ __forceinline__ float bf_hi(unsigned w) { return __uint_as_float(w & 0xffff0000u); }
; __device__ __forceinline__ u32x4 pack8(f32x4 a, f32x4 b) { u32x4 w; w.x = cvt_pk_bf16(a[0], a[1]); w.y = cvt_pk_bf16(a[2], a[3]); w.z = cvt_pk_bf16(b[0], b[1]); w.w = cvt_pk_bf16(b[2], b[3]); return w; }
;     __device__ __forceinline__ void operator()(f32x4 (&acc)[2][2][4][2], const Unit& u, int wr, int wc, int fr, int fq) const {
;     ...
;                 const int row = row0 + ai * HALF + m * 16; float sq = 0.f;
; #pragma unroll
;                 for (int bj = 0; bj < 2; ++bj) {
;                     const size_t off = (size_t)row * D + col0 + bj * 32;
;                     const u32x4 xw = *(const u32x4*)(xin + off);
;                     const f32x4 v0 = acc[ai][bj][m][0] + (f32x4){bf_lo(xw.x), bf_hi(xw.x), bf_lo(xw.y), bf_hi(xw.y)}, v1 = acc[ai][bj][m][1] + (f32x4){bf_lo(xw.z), bf_hi(xw.z), bf_lo(xw.w), bf_hi(xw.w)};
;                     *(u32x4*)(xb + off) = pack8(v0, v1);
;                     sq += (v0[0] * v0[0] + v0[1] * v0[1]) + (v0[2] * v0[2] + v0[3] * v0[3]) + (v1[0] * v1[0] + v1[1] * v1[1]) + (v1[2] * v1[2] + v1[3] * v1[3]);
;                 }
	v_lshlrev_b32_e32 v246, 16, v198
	v_and_b32_e32 v247, 0xffff0000, v198
	v_lshlrev_b32_e32 v248, 16, v199
	v_and_b32_e32 v249, 0xffff0000, v199
	v_pk_add_f32 v[78:79], v[78:79], v[246:247]
	v_pk_add_f32 v[80:81], v[80:81], v[248:249]
	v_lshlrev_b32_e32 v246, 16, v200
	v_and_b32_e32 v247, 0xffff0000, v200
	v_lshlrev_b32_e32 v248, 16, v201
	v_and_b32_e32 v249, 0xffff0000, v201
	v_pk_add_f32 v[74:75], v[74:75], v[246:247]
	v_pk_add_f32 v[76:77], v[76:77], v[248:249]
	v_cvt_pk_bf16_f32 v198, v78, v79
	v_cvt_pk_bf16_f32 v199, v80, v81
	v_cvt_pk_bf16_f32 v200, v74, v75
	v_cvt_pk_bf16_f32 v201, v76, v77
	global_store_dwordx4 v153, v[198:201], s[44:45]
	v_pk_mul_f32 v[250:251], v[78:79], v[78:79]
	v_pk_fma_f32 v[250:251], v[80:81], v[80:81], v[250:251]
	v_pk_fma_f32 v[250:251], v[74:75], v[74:75], v[250:251]
	v_pk_fma_f32 v[250:251], v[76:77], v[76:77], v[250:251]
	s_waitcnt vmcnt(15)
	v_lshlrev_b32_e32 v246, 16, v202
	v_and_b32_e32 v247, 0xffff0000, v202
	v_lshlrev_b32_e32 v248, 16, v203
	v_and_b32_e32 v249, 0xffff0000, v203
	v_pk_add_f32 v[70:71], v[70:71], v[246:247]
	v_pk_add_f32 v[72:73], v[72:73], v[248:249]
	v_lshlrev_b32_e32 v246, 16, v204
	v_and_b32_e32 v247, 0xffff0000, v204
	v_lshlrev_b32_e32 v248, 16, v205
	v_and_b32_e32 v249, 0xffff0000, v205
	v_pk_add_f32 v[66:67], v[66:67], v[246:247]
	v_pk_add_f32 v[68:69], v[68:69], v[248:249]
	v_cvt_pk_bf16_f32 v202, v70, v71
	v_cvt_pk_bf16_f32 v203, v72, v73
	v_cvt_pk_bf16_f32 v204, v66, v67
	v_cvt_pk_bf16_f32 v205, v68, v69
	global_store_dwordx4 v153, v[202:205], s[44:45] offset:64
	v_pk_fma_f32 v[250:251], v[70:71], v[70:71], v[250:251]
	v_pk_fma_f32 v[250:251], v[72:73], v[72:73], v[250:251]
	v_pk_fma_f32 v[250:251], v[66:67], v[66:67], v[250:251]
	v_pk_fma_f32 v[250:251], v[68:69], v[68:69], v[250:251]
	v_add_f32_e32 v143, v250, v251
	s_waitcnt vmcnt(15)
	v_lshlrev_b32_e32 v246, 16, v206
	v_and_b32_e32 v247, 0xffff0000, v206
	v_lshlrev_b32_e32 v248, 16, v207
	v_and_b32_e32 v249, 0xffff0000, v207
	v_pk_add_f32 v[62:63], v[62:63], v[246:247]
	v_pk_add_f32 v[64:65], v[64:65], v[248:249]
	v_lshlrev_b32_e32 v246, 16, v208
	v_and_b32_e32 v247, 0xffff0000, v208
	v_lshlrev_b32_e32 v248, 16, v209
	v_and_b32_e32 v249, 0xffff0000, v209
	v_pk_add_f32 v[58:59], v[58:59], v[246:247]
	v_pk_add_f32 v[60:61], v[60:61], v[248:249]
	v_cvt_pk_bf16_f32 v206, v62, v63
	v_cvt_pk_bf16_f32 v207, v64, v65
	v_cvt_pk_bf16_f32 v208, v58, v59
	v_cvt_pk_bf16_f32 v209, v60, v61
	global_store_dwordx4 v154, v[206:209], s[44:45]
	v_pk_mul_f32 v[250:251], v[62:63], v[62:63]
	v_pk_fma_f32 v[250:251], v[64:65], v[64:65], v[250:251]
	v_pk_fma_f32 v[250:251], v[58:59], v[58:59], v[250:251]
	v_pk_fma_f32 v[250:251], v[60:61], v[60:61], v[250:251]
	s_waitcnt vmcnt(15)
	v_lshlrev_b32_e32 v246, 16, v210
	v_and_b32_e32 v247, 0xffff0000, v210
	v_lshlrev_b32_e32 v248, 16, v211
	v_and_b32_e32 v249, 0xffff0000, v211
	v_pk_add_f32 v[54:55], v[54:55], v[246:247]
	v_pk_add_f32 v[56:57], v[56:57], v[248:249]
	v_lshlrev_b32_e32 v246, 16, v212
	v_and_b32_e32 v247, 0xffff0000, v212
	v_lshlrev_b32_e32 v248, 16, v213
	v_and_b32_e32 v249, 0xffff0000, v213
	v_pk_add_f32 v[50:51], v[50:51], v[246:247]
	v_pk_add_f32 v[52:53], v[52:53], v[248:249]
	v_cvt_pk_bf16_f32 v210, v54, v55
	v_cvt_pk_bf16_f32 v211, v56, v57
	v_cvt_pk_bf16_f32 v212, v50, v51
	v_cvt_pk_bf16_f32 v213, v52, v53
	global_store_dwordx4 v154, v[210:213], s[44:45] offset:64
	v_pk_fma_f32 v[250:251], v[54:55], v[54:55], v[250:251]
	v_pk_fma_f32 v[250:251], v[56:57], v[56:57], v[250:251]
	v_pk_fma_f32 v[250:251], v[50:51], v[50:51], v[250:251]
	v_pk_fma_f32 v[250:251], v[52:53], v[52:53], v[250:251]
	v_add_f32_e32 v144, v250, v251
	s_waitcnt vmcnt(15)
	v_lshlrev_b32_e32 v246, 16, v214
	v_and_b32_e32 v247, 0xffff0000, v214
	v_lshlrev_b32_e32 v248, 16, v215
	v_and_b32_e32 v249, 0xffff0000, v215
	v_pk_add_f32 v[46:47], v[46:47], v[246:247]
	v_pk_add_f32 v[48:49], v[48:49], v[248:249]
	v_lshlrev_b32_e32 v246, 16, v216
	v_and_b32_e32 v247, 0xffff0000, v216
	v_lshlrev_b32_e32 v248, 16, v217
	v_and_b32_e32 v249, 0xffff0000, v217
	v_pk_add_f32 v[42:43], v[42:43], v[246:247]
	v_pk_add_f32 v[44:45], v[44:45], v[248:249]
	v_cvt_pk_bf16_f32 v214, v46, v47
	v_cvt_pk_bf16_f32 v215, v48, v49
	v_cvt_pk_bf16_f32 v216, v42, v43
	v_cvt_pk_bf16_f32 v217, v44, v45
	global_store_dwordx4 v155, v[214:217], s[44:45]
	v_pk_mul_f32 v[250:251], v[46:47], v[46:47]
	v_pk_fma_f32 v[250:251], v[48:49], v[48:49], v[250:251]
	v_pk_fma_f32 v[250:251], v[42:43], v[42:43], v[250:251]
	v_pk_fma_f32 v[250:251], v[44:45], v[44:45], v[250:251]
	s_waitcnt vmcnt(15)
	v_lshlrev_b32_e32 v246, 16, v218
	v_and_b32_e32 v247, 0xffff0000, v218
	v_lshlrev_b32_e32 v248, 16, v219
	v_and_b32_e32 v249, 0xffff0000, v219
	v_pk_add_f32 v[38:39], v[38:39], v[246:247]
	v_pk_add_f32 v[40:41], v[40:41], v[248:249]
	v_lshlrev_b32_e32 v246, 16, v220
	v_and_b32_e32 v247, 0xffff0000, v220
	v_lshlrev_b32_e32 v248, 16, v221
	v_and_b32_e32 v249, 0xffff0000, v221
	v_pk_add_f32 v[34:35], v[34:35], v[246:247]
	v_pk_add_f32 v[36:37], v[36:37], v[248:249]
	v_cvt_pk_bf16_f32 v218, v38, v39
	v_cvt_pk_bf16_f32 v219, v40, v41
	v_cvt_pk_bf16_f32 v220, v34, v35
	v_cvt_pk_bf16_f32 v221, v36, v37
	global_store_dwordx4 v155, v[218:221], s[44:45] offset:64
	v_pk_fma_f32 v[250:251], v[38:39], v[38:39], v[250:251]
	v_pk_fma_f32 v[250:251], v[40:41], v[40:41], v[250:251]
	v_pk_fma_f32 v[250:251], v[34:35], v[34:35], v[250:251]
	v_pk_fma_f32 v[250:251], v[36:37], v[36:37], v[250:251]
	v_add_f32_e32 v145, v250, v251
	s_waitcnt vmcnt(15)
; #define PG8_BAR __builtin_amdgcn_s_barrier()
; template <class Epi, class SchedT, bool ALIGN_EPI, bool SP2>
; __device__ __forceinline__ void gemm_phase(LAS unsigned char* lds, const int ldk, const int nt, const SchedT& S, const Epi& E) {
;     ...
;         if (!has_next) break;
;         if (!(SchedT::kMode == 2 && cur.kind == 0)) {
; #pragma unroll
;         for (int a = 0; a < 2; ++a)
; #pragma unroll
;             for (int b = 0; b < 2; ++b)
; #pragma unroll
;                 for (int m = 0; m < 4; ++m)
; #pragma unroll
;                     for (int n = 0; n < 2; ++n) acc[a][b][m][n] = (f32x4){0.f, 0.f, 0.f, 0.f};
;         }
;         cur = nxt; cA = nA; cB = nB; ++ui;
;         if constexpr (ALIGN_EPI) { if (wr == 1) PG8_BAR; }
;     __device__ __forceinline__ void operator()(f32x4 (&acc)[2][2][4][2], const Unit& u, int wr, int wc, int fr, int fq) const {
;     ...
;                     sq += (v0[0] * v0[0] + v0[1] * v0[1]) + (v0[2] * v0[2] + v0[3] * v0[3]) + (v1[0] * v1[0] + v1[1] * v1[1]) + (v1[2] * v1[2] + v1[3] * v1[3]);
;                 }
;                 sq += __shfl_xor(sq, 16); sq += __shfl_xor(sq, 32);
;                 if (fq == 0) ss[(size_t)row * 32 + u.pn * 4 + wc] = sq;
;             }
	v_lshlrev_b32_e32 v246, 16, v222
	v_and_b32_e32 v247, 0xffff0000, v222
	v_lshlrev_b32_e32 v248, 16, v223
	v_and_b32_e32 v249, 0xffff0000, v223
	v_pk_add_f32 v[30:31], v[30:31], v[246:247]
	v_pk_add_f32 v[32:33], v[32:33], v[248:249]
	v_lshlrev_b32_e32 v246, 16, v224
	v_and_b32_e32 v247, 0xffff0000, v224
	v_lshlrev_b32_e32 v248, 16, v225
	v_and_b32_e32 v249, 0xffff0000, v225
	v_pk_add_f32 v[26:27], v[26:27], v[246:247]
	v_pk_add_f32 v[28:29], v[28:29], v[248:249]
	v_cvt_pk_bf16_f32 v222, v30, v31
	v_cvt_pk_bf16_f32 v223, v32, v33
	v_cvt_pk_bf16_f32 v224, v26, v27
	v_cvt_pk_bf16_f32 v225, v28, v29
	global_store_dwordx4 v156, v[222:225], s[44:45]
	v_pk_mul_f32 v[250:251], v[30:31], v[30:31]
	v_pk_fma_f32 v[250:251], v[32:33], v[32:33], v[250:251]
	v_pk_fma_f32 v[250:251], v[26:27], v[26:27], v[250:251]
	v_pk_fma_f32 v[250:251], v[28:29], v[28:29], v[250:251]
	s_waitcnt vmcnt(15)
	v_lshlrev_b32_e32 v246, 16, v226
	v_and_b32_e32 v247, 0xffff0000, v226
	v_lshlrev_b32_e32 v248, 16, v227
	v_and_b32_e32 v249, 0xffff0000, v227
	v_pk_add_f32 v[22:23], v[22:23], v[246:247]
	v_pk_add_f32 v[24:25], v[24:25], v[248:249]
	v_lshlrev_b32_e32 v246, 16, v228
	v_and_b32_e32 v247, 0xffff0000, v228
	v_lshlrev_b32_e32 v248, 16, v229
	v_and_b32_e32 v249, 0xffff0000, v229
	v_pk_add_f32 v[18:19], v[18:19], v[246:247]
	v_pk_add_f32 v[20:21], v[20:21], v[248:249]
	v_cvt_pk_bf16_f32 v226, v22, v23
	v_cvt_pk_bf16_f32 v227, v24, v25
	v_cvt_pk_bf16_f32 v228, v18, v19
	v_cvt_pk_bf16_f32 v229, v20, v21
	global_store_dwordx4 v156, v[226:229], s[44:45] offset:64
	v_pk_fma_f32 v[250:251], v[22:23], v[22:23], v[250:251]
	v_pk_fma_f32 v[250:251], v[24:25], v[24:25], v[250:251]
	v_pk_fma_f32 v[250:251], v[18:19], v[18:19], v[250:251]
	v_pk_fma_f32 v[250:251], v[20:21], v[20:21], v[250:251]
	v_add_f32_e32 v162, v250, v251
	s_waitcnt vmcnt(15)
	v_lshlrev_b32_e32 v246, 16, v230
	v_and_b32_e32 v247, 0xffff0000, v230
	v_lshlrev_b32_e32 v248, 16, v231
	v_and_b32_e32 v249, 0xffff0000, v231
	v_pk_add_f32 v[14:15], v[14:15], v[246:247]
	v_pk_add_f32 v[16:17], v[16:17], v[248:249]
	v_lshlrev_b32_e32 v246, 16, v232
	v_and_b32_e32 v247, 0xffff0000, v232
	v_lshlrev_b32_e32 v248, 16, v233
	v_and_b32_e32 v249, 0xffff0000, v233
	v_pk_add_f32 v[10:11], v[10:11], v[246:247]
	v_pk_add_f32 v[12:13], v[12:13], v[248:249]
	v_cvt_pk_bf16_f32 v230, v14, v15
	v_cvt_pk_bf16_f32 v231, v16, v17
	v_cvt_pk_bf16_f32 v232, v10, v11
	v_cvt_pk_bf16_f32 v233, v12, v13
	global_store_dwordx4 v157, v[230:233], s[44:45]
	v_pk_mul_f32 v[250:251], v[14:15], v[14:15]
	v_pk_fma_f32 v[250:251], v[16:17], v[16:17], v[250:251]
	v_pk_fma_f32 v[250:251], v[10:11], v[10:11], v[250:251]
	v_pk_fma_f32 v[250:251], v[12:13], v[12:13], v[250:251]
	s_waitcnt vmcnt(15)
	v_lshlrev_b32_e32 v246, 16, v234
	v_and_b32_e32 v247, 0xffff0000, v234
	v_lshlrev_b32_e32 v248, 16, v235
	v_and_b32_e32 v249, 0xffff0000, v235
	v_pk_add_f32 v[6:7], v[6:7], v[246:247]
	v_pk_add_f32 v[8:9], v[8:9], v[248:249]
	v_lshlrev_b32_e32 v246, 16, v236
	v_and_b32_e32 v247, 0xffff0000, v236
	v_lshlrev_b32_e32 v248, 16, v237
	v_and_b32_e32 v249, 0xffff0000, v237
	v_pk_add_f32 v[2:3], v[2:3], v[246:247]
	v_pk_add_f32 v[4:5], v[4:5], v[248:249]
	v_cvt_pk_bf16_f32 v234, v6, v7
	v_cvt_pk_bf16_f32 v235, v8, v9
	v_cvt_pk_bf16_f32 v236, v2, v3
	v_cvt_pk_bf16_f32 v237, v4, v5
	global_store_dwordx4 v157, v[234:237], s[44:45] offset:64
	v_pk_fma_f32 v[250:251], v[6:7], v[6:7], v[250:251]
	v_pk_fma_f32 v[250:251], v[8:9], v[8:9], v[250:251]
	v_pk_fma_f32 v[250:251], v[2:3], v[2:3], v[250:251]
	v_pk_fma_f32 v[250:251], v[4:5], v[4:5], v[250:251]
	v_add_f32_e32 v238, v250, v251
	ds_bpermute_b32 v174, v239, v140
	ds_bpermute_b32 v175, v239, v141
	ds_bpermute_b32 v176, v239, v142
	ds_bpermute_b32 v177, v239, v143
	ds_bpermute_b32 v178, v239, v144
	ds_bpermute_b32 v179, v239, v145
	ds_bpermute_b32 v180, v239, v162
	ds_bpermute_b32 v181, v239, v238
	s_waitcnt lgkmcnt(0)
	v_add_f32_e32 v140, v140, v174
	v_add_f32_e32 v141, v141, v175
	v_add_f32_e32 v142, v142, v176
	v_add_f32_e32 v143, v143, v177
	v_add_f32_e32 v144, v144, v178
	v_add_f32_e32 v145, v145, v179
	v_add_f32_e32 v162, v162, v180
	v_add_f32_e32 v238, v238, v181
	ds_bpermute_b32 v174, v252, v140
	ds_bpermute_b32 v175, v252, v141
	ds_bpermute_b32 v176, v252, v142
	ds_bpermute_b32 v177, v252, v143
	ds_bpermute_b32 v178, v252, v144
	ds_bpermute_b32 v179, v252, v145
	ds_bpermute_b32 v180, v252, v162
	ds_bpermute_b32 v181, v252, v238
	s_waitcnt lgkmcnt(0)
	v_add_f32_e32 v140, v140, v174
	v_add_f32_e32 v141, v141, v175
	v_add_f32_e32 v142, v142, v176
	v_add_f32_e32 v143, v143, v177
	v_add_f32_e32 v144, v144, v178
	v_add_f32_e32 v145, v145, v179
	v_add_f32_e32 v162, v162, v180
	v_add_f32_e32 v238, v238, v181
	s_and_saveexec_b64 s[12:13], s[38:39]
	global_store_dword v158, v140, s[46:47]
	global_store_dword v158, v141, s[46:47] offset:2048
	global_store_dword v159, v142, s[46:47]
	global_store_dword v159, v143, s[46:47] offset:2048
	global_store_dword v160, v144, s[46:47]
	global_store_dword v160, v145, s[46:47] offset:2048
	global_store_dword v161, v162, s[46:47]
	global_store_dword v161, v238, s[46:47] offset:2048
	s_mov_b32 s86, 0x20000
	s_mov_b32 s87, 0x28000
	s_or_b64 exec, exec, s[12:13]
	s_and_b64 vcc, exec, s[40:41]
	s_mov_b64 s[12:13], -1
	s_cbranch_vccnz .LBB0_662
	s_setprio 2
	s_andn2_b64 vcc, exec, s[18:19]
	s_cbranch_vccnz .LBB0_661
	s_barrier
	s_setprio 3
	s_branch .LBB0_661

; #define PG8_STAGE(bufoff, gbase, voff) do { _Pragma("unroll") for (int _i = 0; _i < 2; ++_i) \
;         __builtin_amdgcn_global_load_lds((const __attribute__((address_space(1))) unsigned*)((const char*)(gbase) + (voff)[_i]), (LAS unsigned*)(lds + (bufoff) + ldsw + _i * 8192), 16, 0, 0); } while (0)
; #define PG8_BAR __builtin_amdgcn_s_barrier()
; template <class Epi, class SchedT, bool ALIGN_EPI, bool SP2>
; __device__ __forceinline__ void gemm_phase(LAS unsigned char* lds, const int ldk, const int nt, const SchedT& S, const Epi& E) {
;     ...
;     for (int i = 0; i < 2; ++i) { int R, C; stage_rc(tid * 16 + i * 8192, R, C); const int Rb = 2 * (R & ~31) + perm32(R & 31);
;         voffA[i] = (unsigned)(R * K + C) * 2u; voffB[i] = (unsigned)(Rb * K + C) * 2u; }
;     const size_t kstep = (size_t)(BK * 2);
;     const size_t hstep = (size_t)HALF * K * 2;
;     const size_t hstepB = (size_t)32 * K * 2;
;     const unsigned ldsw = (unsigned)wid * 1024u;
;     const int aoff = lds_byte(wr * 64 + fr, fq * 8), boff = lds_byte(wc * 32 + fr, fq * 8);
;     ...
;     Unit cur, nxt; int ui = 0;
;     if (!S.next(0, cur)) return;
;     f32x4 acc[2][2][4][2];
; #pragma unroll
;     for (int a = 0; a < 2; ++a)
; #pragma unroll
;         for (int b = 0; b < 2; ++b)
; #pragma unroll
;             for (int m = 0; m < 4; ++m)
; #pragma unroll
;                 for (int n = 0; n < 2; ++n) acc[a][b][m][n] = (f32x4){0.f, 0.f, 0.f, 0.f};
;     bf16x8 At[4][2], B0[2][2], B1[2][2];
;     const char* cA; const char* cB; S.ptrs(cur, cA, cB);
;     if constexpr (SP2) {
;         PG8_STAGE(PG8_SB(0, 0), cB, voffB); PG8_STAGE(PG8_SB(0, 1), cB + hstepB, voffB); PG8_STAGE(PG8_SA(0, 0), cA, voffA); PG8_STAGE(PG8_SA(0, 1), cA + hstep, voffA);
;         if (wr == 1) PG8_BAR;
.LBB0_741:
	v_readlane_b32 s18, v163, 39
	v_readlane_b32 s44, v254, 1
	s_mul_i32 s13, s18, 0x20400
	v_readlane_b32 s52, v254, 9
	v_readlane_b32 s19, v163, 40
	s_mov_b32 s20, s18
	v_readlane_b32 s53, v254, 10
	s_add_u32 s18, s52, s13
	v_readlane_b32 s54, v254, 11
	s_addc_u32 s19, s53, 0
	s_mul_i32 s13, s20, 0xac00
	v_readlane_b32 s55, v254, 12
	s_add_u32 s20, s54, s13
	s_addc_u32 s21, s55, 0
	s_and_b64 vcc, exec, s[0:1]
	v_readlane_b32 s45, v254, 2
	v_readlane_b32 s46, v254, 3
	v_readlane_b32 s47, v254, 4
	v_readlane_b32 s48, v254, 5
	v_readlane_b32 s49, v254, 6
	v_readlane_b32 s50, v254, 7
	v_readlane_b32 s51, v254, 8
	v_readlane_b32 s56, v254, 13
	v_readlane_b32 s57, v254, 14
	v_readlane_b32 s58, v254, 15
	v_readlane_b32 s59, v254, 16
	s_cbranch_vccnz .LBB0_791
	v_ashrrev_i32_e32 v0, 31, v16
	v_lshrrev_b32_e32 v0, 26, v0
	v_add_u32_e32 v0, v16, v0
	v_ashrrev_i32_e32 v10, 6, v0
	v_bfe_i32 v0, v16, 27, 1
	v_lshlrev_b32_e32 v2, 4, v16
	v_lshrrev_b32_e32 v0, 22, v0
	v_add_u32_e32 v0, v2, v0
	v_and_b32_e32 v0, 0xfffffc00, v0
	v_sub_u32_e32 v0, v2, v0
	v_lshrrev_b32_e32 v3, 4, v0
	v_bitop3_b32 v0, v3, v0, 32 bitop3:0x6c
	v_ashrrev_i32_e32 v4, 31, v0
	v_lshrrev_b32_e32 v4, 26, v4
	v_add_u32_e32 v4, v0, v4
	v_lshlrev_b32_e32 v3, 3, v10
	v_ashrrev_i32_e32 v11, 6, v4
	v_and_b32_e32 v4, 0xc0, v4
	v_and_b32_e32 v3, -16, v3
	v_sub_u32_e32 v0, v0, v4
	v_add_u32_e32 v3, v11, v3
	v_ashrrev_i16_sdwa v0, v244, sext(v0) dst_sel:DWORD dst_unused:UNUSED_PAD src0_sel:DWORD src1_sel:BYTE_0
	v_lshlrev_b32_e32 v5, 5, v10
	v_bfe_i32 v12, v0, 0, 16
	v_lshlrev_b32_e32 v0, 1, v3
	v_lshrrev_b32_e32 v4, 2, v3
	v_and_b32_e32 v5, 32, v5
	v_and_b32_e32 v4, 4, v4
	v_and_b32_e32 v6, 3, v11
	v_and_b32_e32 v0, 0xfffd8, v0
	v_or3_b32 v0, v6, v4, v0
	v_add_lshl_u32 v4, v5, v12, 1
	v_add_u32_e32 v2, 0x2000, v2
	v_lshl_add_u32 v146, v3, 12, v4
	v_ashrrev_i32_e32 v3, 31, v2
	v_lshrrev_b32_e32 v3, 22, v3
	v_add_u32_e32 v3, v2, v3
	v_ashrrev_i32_e32 v13, 10, v3
	v_mul_i32_i24_e32 v3, 0x400, v13
	v_readlane_b32 s0, v163, 36
	v_sub_u32_e32 v2, v2, v3
	s_add_u32 s0, s38, s0
	v_lshrrev_b32_e32 v3, 4, v2
	s_addc_u32 s1, s39, 0
	v_bitop3_b32 v2, v3, v2, 32 bitop3:0x6c
	s_add_u32 s22, s38, 0x10c00000
	v_lshl_add_u32 v0, v0, 12, v4
	v_ashrrev_i32_e32 v4, 31, v2
	s_addc_u32 s81, s39, 0
	v_lshrrev_b32_e32 v4, 26, v4
	s_add_u32 s82, s0, 0x3600000
	v_add_u32_e32 v4, v2, v4
	s_addc_u32 s83, s1, 0
	v_lshlrev_b32_e32 v3, 3, v13
	v_ashrrev_i32_e32 v14, 6, v4
	v_and_b32_e32 v4, 0xc0, v4
	s_ashr_i32 s41, s40, 6
	s_ashr_i32 s13, s12, 31
	s_ashr_i32 s17, s16, 31
	s_ashr_i32 s50, s40, 8
	v_and_b32_e32 v3, -16, v3
	v_sub_u32_e32 v2, v2, v4
	s_lshl_b32 s84, s41, 10
	s_lshl_b64 s[0:1], s[12:13], 20
	s_lshl_b64 s[34:35], s[16:17], 20
	v_add_u32_e32 v3, v14, v3
	v_ashrrev_i16_sdwa v2, v244, sext(v2) dst_sel:DWORD dst_unused:UNUSED_PAD src0_sel:DWORD src1_sel:BYTE_0
	s_add_u32 s36, s82, s34
	v_lshlrev_b32_e32 v5, 5, v13
	v_bfe_i32 v15, v2, 0, 16
	v_lshlrev_b32_e32 v2, 1, v3
	v_lshrrev_b32_e32 v4, 2, v3
	s_addc_u32 s37, s83, s35
	s_add_i32 s85, s84, 0
	v_and_b32_e32 v5, 32, v5
	v_and_b32_e32 v4, 4, v4
	v_and_b32_e32 v6, 3, v14
	v_and_b32_e32 v2, 0xfffd8, v2
	s_add_i32 m0, s85, 0x10000
	v_or3_b32 v2, v6, v4, v2
	v_add_lshl_u32 v4, v5, v15, 1
	global_load_lds_dwordx4 v0, s[36:37]
	s_add_i32 m0, s85, 0x12000
	v_lshl_add_u32 v150, v2, 12, v4
	s_add_u32 s34, s36, 0x20000
	global_load_lds_dwordx4 v150, s[36:37]
	s_addc_u32 s35, s37, 0
	s_add_i32 m0, s85, 0x14000
	v_lshl_add_u32 v148, v3, 12, v4
	global_load_lds_dwordx4 v0, s[34:35]
	s_add_i32 m0, s85, 0x16000
	v_mov_b32_e32 v151, v1
	global_load_lds_dwordx4 v150, s[34:35]
	s_add_u32 s34, s22, s0
	s_addc_u32 s35, s81, s1
	s_add_i32 s86, s85, 0x2000
	s_mov_b32 m0, s85
	s_add_u32 s0, s34, 0x80000
	global_load_lds_dwordx4 v146, s[34:35]
	s_mov_b32 m0, s86
	s_addc_u32 s1, s35, 0
	s_add_i32 s87, s85, 0x4000
	global_load_lds_dwordx4 v148, s[34:35]
	s_mov_b32 m0, s87
	s_add_i32 s88, s85, 0x6000
	global_load_lds_dwordx4 v146, s[0:1]
	s_mov_b32 m0, s88
	v_mov_b32_e32 v147, v1
	global_load_lds_dwordx4 v148, s[0:1]
	v_mov_b32_e32 v149, v1
	s_cmp_eq_u32 s50, 1
	v_mov_b32_e32 v162, v242
	v_lshl_add_u64 v[8:9], s[36:37], 0, v[0:1]
	v_lshl_add_u64 v[6:7], s[36:37], 0, v[150:151]
	v_lshl_add_u64 v[2:3], s[34:35], 0, v[146:147]
	s_cselect_b64 s[52:53], -1, 0
	s_cmp_lg_u32 s50, 1
	v_lshl_add_u64 v[4:5], s[34:35], 0, v[148:149]
	s_setprio 2
	s_cbranch_scc1 .LBB0_744
	s_barrier
	s_setprio 3

; #define PG8_BAR __builtin_amdgcn_s_barrier()
; template <class Epi, class SchedT, bool ALIGN_EPI, bool SP2>
; __device__ __forceinline__ void gemm_phase(LAS unsigned char* lds, const int ldk, const int nt, const SchedT& S, const Epi& E) {
;     ...
;         if (!has_next) break;
;         if (!(SchedT::kMode == 2 && cur.kind == 0)) {
; #pragma unroll
;         for (int a = 0; a < 2; ++a)
; #pragma unroll
;             for (int b = 0; b < 2; ++b)
; #pragma unroll
;                 for (int m = 0; m < 4; ++m)
; #pragma unroll
;                     for (int n = 0; n < 2; ++n) acc[a][b][m][n] = (f32x4){0.f, 0.f, 0.f, 0.f};
;         }
;         cur = nxt; cA = nA; cB = nB; ++ui;
;         if constexpr (ALIGN_EPI) { if (wr == 1) PG8_BAR; }
.LBB0_788:
	s_setprio 2
	s_andn2_b64 vcc, exec, s[52:53]
	s_cbranch_vccnz .LBB0_745
	s_barrier
	s_setprio 3
	s_branch .LBB0_745

; #define PG8_STAGE(bufoff, gbase, voff) do { _Pragma("unroll") for (int _i = 0; _i < 2; ++_i) \
;         __builtin_amdgcn_global_load_lds((const __attribute__((address_space(1))) unsigned*)((const char*)(gbase) + (voff)[_i]), (LAS unsigned*)(lds + (bufoff) + ldsw + _i * 8192), 16, 0, 0); } while (0)
; #define PG8_BAR __builtin_amdgcn_s_barrier()
; template <class Epi, class SchedT, bool ALIGN_EPI, bool SP2>
; __device__ __forceinline__ void gemm_phase(LAS unsigned char* lds, const int ldk, const int nt, const SchedT& S, const Epi& E) {
;     ...
;     for (int i = 0; i < 2; ++i) { int R, C; stage_rc(tid * 16 + i * 8192, R, C); const int Rb = 2 * (R & ~31) + perm32(R & 31);
;         voffA[i] = (unsigned)(R * K + C) * 2u; voffB[i] = (unsigned)(Rb * K + C) * 2u; }
;     const size_t kstep = (size_t)(BK * 2);
;     const size_t hstep = (size_t)HALF * K * 2;
;     const size_t hstepB = (size_t)32 * K * 2;
;     const unsigned ldsw = (unsigned)wid * 1024u;
;     const int aoff = lds_byte(wr * 64 + fr, fq * 8), boff = lds_byte(wc * 32 + fr, fq * 8);
;     ...
;     Unit cur, nxt; int ui = 0;
;     if (!S.next(0, cur)) return;
;     f32x4 acc[2][2][4][2];
; #pragma unroll
;     for (int a = 0; a < 2; ++a)
; #pragma unroll
;         for (int b = 0; b < 2; ++b)
; #pragma unroll
;             for (int m = 0; m < 4; ++m)
; #pragma unroll
;                 for (int n = 0; n < 2; ++n) acc[a][b][m][n] = (f32x4){0.f, 0.f, 0.f, 0.f};
;     bf16x8 At[4][2], B0[2][2], B1[2][2];
;     const char* cA; const char* cB; S.ptrs(cur, cA, cB);
;     if constexpr (SP2) {
;         PG8_STAGE(PG8_SB(0, 0), cB, voffB); PG8_STAGE(PG8_SB(0, 1), cB + hstepB, voffB); PG8_STAGE(PG8_SA(0, 0), cA, voffA); PG8_STAGE(PG8_SA(0, 1), cA + hstep, voffA);
;         if (wr == 1) PG8_BAR;
.LBB0_937:
	v_readlane_b32 s12, v163, 43
	v_readlane_b32 s13, v163, 44
	s_and_b64 vcc, exec, s[12:13]
	s_cbranch_vccnz .LBB0_971
	v_ashrrev_i32_e32 v0, 31, v18
	v_lshrrev_b32_e32 v0, 26, v0
	v_add_u32_e32 v0, v18, v0
	v_ashrrev_i32_e32 v10, 6, v0
	v_bfe_i32 v0, v18, 27, 1
	v_lshlrev_b32_e32 v2, 4, v18
	v_lshrrev_b32_e32 v0, 22, v0
	v_add_u32_e32 v0, v2, v0
	v_and_b32_e32 v0, 0xfffffc00, v0
	v_sub_u32_e32 v0, v2, v0
	v_lshrrev_b32_e32 v3, 4, v0
	v_bitop3_b32 v0, v3, v0, 32 bitop3:0x6c
	v_ashrrev_i32_e32 v4, 31, v0
	v_readlane_b32 s12, v163, 36
	v_lshrrev_b32_e32 v4, 26, v4
	s_add_u32 s12, s0, s12
	v_lshlrev_b32_e32 v3, 3, v10
	v_add_u32_e32 v4, v0, v4
	s_addc_u32 s13, s1, 0
	v_and_b32_e32 v3, -16, v3
	v_ashrrev_i32_e32 v12, 6, v4
	v_and_b32_e32 v4, 0xc0, v4
	s_add_u32 s48, s0, 0x21800000
	v_add_u32_e32 v3, v12, v3
	v_lshlrev_b32_e32 v5, 5, v10
	v_sub_u32_e32 v0, v0, v4
	s_addc_u32 s49, s1, 0
	v_and_b32_e32 v11, 32, v5
	v_ashrrev_i16_sdwa v0, v244, sext(v0) dst_sel:DWORD dst_unused:UNUSED_PAD src0_sel:DWORD src1_sel:BYTE_0
	v_lshlrev_b32_e32 v4, 1, v3
	v_lshrrev_b32_e32 v5, 2, v3
	s_add_u32 s50, s12, 0x6100000
	v_bfe_i32 v13, v0, 0, 16
	v_and_b32_e32 v5, 4, v5
	v_and_b32_e32 v6, 3, v12
	v_and_b32_e32 v4, 0x1ffffd8, v4
	s_movk_i32 s12, 0x1580
	v_add_u32_e32 v0, v11, v13
	v_or3_b32 v4, v6, v5, v4
	v_mul_lo_u32 v3, v3, s12
	v_add_lshl_u32 v130, v0, v3, 1
	v_mul_lo_u32 v3, v4, s12
	v_add_u32_e32 v2, 0x2000, v2
	v_add_lshl_u32 v0, v3, v0, 1
	v_ashrrev_i32_e32 v3, 31, v2
	v_lshrrev_b32_e32 v3, 22, v3
	v_add_u32_e32 v3, v2, v3
	v_ashrrev_i32_e32 v14, 10, v3
	v_mul_i32_i24_e32 v3, 0x400, v14
	v_sub_u32_e32 v2, v2, v3
	v_lshrrev_b32_e32 v3, 4, v2
	v_bitop3_b32 v2, v3, v2, 32 bitop3:0x6c
	v_ashrrev_i32_e32 v4, 31, v2
	v_lshrrev_b32_e32 v4, 26, v4
	v_lshlrev_b32_e32 v3, 3, v14
	v_add_u32_e32 v4, v2, v4
	v_and_b32_e32 v3, -16, v3
	v_ashrrev_i32_e32 v16, 6, v4
	v_and_b32_e32 v4, 0xc0, v4
	v_add_u32_e32 v3, v16, v3
	v_lshlrev_b32_e32 v5, 5, v14
	v_sub_u32_e32 v2, v2, v4
	v_and_b32_e32 v15, 32, v5
	v_ashrrev_i16_sdwa v2, v244, sext(v2) dst_sel:DWORD dst_unused:UNUSED_PAD src0_sel:DWORD src1_sel:BYTE_0
	v_lshlrev_b32_e32 v4, 1, v3
	v_lshrrev_b32_e32 v5, 2, v3
	s_addc_u32 s51, s13, 0
	s_ashr_i32 s37, s36, 6
	v_bfe_i32 v17, v2, 0, 16
	v_and_b32_e32 v5, 4, v5
	v_and_b32_e32 v6, 3, v16
	v_and_b32_e32 v4, 0x1ffffd8, v4
	v_add_u32_e32 v2, v15, v17
	v_or3_b32 v4, v6, v5, v4
	v_mul_lo_u32 v3, v3, s12
	s_ashr_i32 s38, s36, 8
	s_lshl_b32 s52, s37, 10
	s_mul_i32 s13, s22, 0x2b0000
	v_add_lshl_u32 v132, v2, v3, 1
	v_mul_lo_u32 v3, v4, s12
	s_mul_hi_i32 s12, s22, 0x2b0000
	s_add_u32 s16, s50, s13
	s_addc_u32 s17, s51, s12
	s_add_i32 s53, s52, 0
	s_add_i32 m0, s53, 0x10000
	v_add_lshl_u32 v134, v3, v2, 1
	global_load_lds_dwordx4 v0, s[16:17]
	s_add_i32 m0, s53, 0x12000
	s_add_u32 s12, s16, 0x56000
	global_load_lds_dwordx4 v134, s[16:17]
	s_addc_u32 s13, s17, 0
	s_add_i32 m0, s53, 0x14000
	s_mul_i32 s19, s63, 0x2b0000
	global_load_lds_dwordx4 v0, s[12:13]
	s_add_i32 m0, s53, 0x16000
	s_mul_hi_i32 s18, s63, 0x2b0000
	global_load_lds_dwordx4 v134, s[12:13]
	s_add_u32 s12, s48, s19
	s_addc_u32 s13, s49, s18
	s_add_i32 s54, s53, 0x2000
	s_mov_b32 m0, s53
	s_add_u32 s18, s12, 0x158000
	global_load_lds_dwordx4 v130, s[12:13]
	s_mov_b32 m0, s54
	s_addc_u32 s19, s13, 0
	s_add_i32 s55, s53, 0x4000
	global_load_lds_dwordx4 v132, s[12:13]
	s_mov_b32 m0, s55
	s_add_i32 s56, s53, 0x6000
	global_load_lds_dwordx4 v130, s[18:19]
	s_mov_b32 m0, s56
	v_mov_b32_e32 v135, v1
	global_load_lds_dwordx4 v132, s[18:19]
	v_mov_b32_e32 v131, v1
	v_mov_b32_e32 v133, v1
	s_cmp_eq_u32 s38, 1
	v_lshl_add_u64 v[8:9], s[16:17], 0, v[0:1]
	v_lshl_add_u64 v[6:7], s[16:17], 0, v[134:135]
	v_lshl_add_u64 v[2:3], s[12:13], 0, v[130:131]
	s_cselect_b64 s[18:19], -1, 0
	s_cmp_lg_u32 s38, 1
	v_lshl_add_u64 v[4:5], s[12:13], 0, v[132:133]
	s_setprio 2
	s_cbranch_scc1 .LBB0_940
	s_barrier
	s_setprio 3

; __device__ __forceinline__ float bf_lo(unsigned w) { return __uint_as_float(w << 16); }
; __device__ __forceinline__ float bf_hi(unsigned w) { return __uint_as_float(w & 0xffff0000u); }
; __device__ __forceinline__ u32x4 pack8(f32x4 a, f32x4 b) { u32x4 w; w.x = cvt_pk_bf16(a[0], a[1]); w.y = cvt_pk_bf16(a[2], a[3]); w.z = cvt_pk_bf16(b[0], b[1]); w.w = cvt_pk_bf16(b[2], b[3]); return w; }
;     __device__ __forceinline__ void operator()(f32x4 (&acc)[2][2][4][2], const Unit& u, int wr, int wc, int fr, int fq) const {
;     ...
;         for (int ai = 0; ai < 2; ++ai)
; #pragma unroll
;             for (int m = 0; m < 4; ++m) {
;                 const int row = row0 + ai * HALF + m * 16; float sq = 0.f;
; #pragma unroll
;                 for (int bj = 0; bj < 2; ++bj) {
;                     const size_t off = (size_t)row * D + col0 + bj * 32;
;                     const u32x4 xw = *(const u32x4*)(xin + off);
;                     const f32x4 v0 = acc[ai][bj][m][0] + (f32x4){bf_lo(xw.x), bf_hi(xw.x), bf_lo(xw.y), bf_hi(xw.y)}, v1 = acc[ai][bj][m][1] + (f32x4){bf_lo(xw.z), bf_hi(xw.z), bf_lo(xw.w), bf_hi(xw.w)};
;                     *(u32x4*)(xb + off) = pack8(v0, v1);
;                     sq += (v0[0] * v0[0] + v0[1] * v0[1]) + (v0[2] * v0[2] + v0[3] * v0[3]) + (v1[0] * v1[0] + v1[1] * v1[1]) + (v1[2] * v1[2] + v1[3] * v1[3]);
;                 }
.LBB0_951:
	s_waitcnt vmcnt(15)
	v_lshlrev_b32_e32 v246, 16, v174
	v_and_b32_e32 v247, 0xffff0000, v174
	v_lshlrev_b32_e32 v248, 16, v175
	v_and_b32_e32 v249, 0xffff0000, v175
	v_pk_add_f32 v[126:127], v[126:127], v[246:247]
	v_pk_add_f32 v[128:129], v[128:129], v[248:249]
	v_lshlrev_b32_e32 v246, 16, v176
	v_and_b32_e32 v247, 0xffff0000, v176
	v_lshlrev_b32_e32 v248, 16, v177
	v_and_b32_e32 v249, 0xffff0000, v177
	v_pk_add_f32 v[122:123], v[122:123], v[246:247]
	v_pk_add_f32 v[124:125], v[124:125], v[248:249]
	v_cvt_pk_bf16_f32 v174, v126, v127
	v_cvt_pk_bf16_f32 v175, v128, v129
	v_cvt_pk_bf16_f32 v176, v122, v123
	v_cvt_pk_bf16_f32 v177, v124, v125
	global_store_dwordx4 v150, v[174:177], s[30:31]
	v_pk_mul_f32 v[250:251], v[126:127], v[126:127]
	v_pk_fma_f32 v[250:251], v[128:129], v[128:129], v[250:251]
	v_pk_fma_f32 v[250:251], v[122:123], v[122:123], v[250:251]
	v_pk_fma_f32 v[250:251], v[124:125], v[124:125], v[250:251]
	s_waitcnt vmcnt(15)
	v_lshlrev_b32_e32 v246, 16, v178
	v_and_b32_e32 v247, 0xffff0000, v178
	v_lshlrev_b32_e32 v248, 16, v179
	v_and_b32_e32 v249, 0xffff0000, v179
	v_pk_add_f32 v[118:119], v[118:119], v[246:247]
	v_pk_add_f32 v[120:121], v[120:121], v[248:249]
	v_lshlrev_b32_e32 v246, 16, v180
	v_and_b32_e32 v247, 0xffff0000, v180
	v_lshlrev_b32_e32 v248, 16, v181
	v_and_b32_e32 v249, 0xffff0000, v181
	v_pk_add_f32 v[114:115], v[114:115], v[246:247]
	v_pk_add_f32 v[116:117], v[116:117], v[248:249]
	v_cvt_pk_bf16_f32 v178, v118, v119
	v_cvt_pk_bf16_f32 v179, v120, v121
	v_cvt_pk_bf16_f32 v180, v114, v115
	v_cvt_pk_bf16_f32 v181, v116, v117
	global_store_dwordx4 v150, v[178:181], s[30:31] offset:64
	v_pk_fma_f32 v[250:251], v[118:119], v[118:119], v[250:251]
	v_pk_fma_f32 v[250:251], v[120:121], v[120:121], v[250:251]
	v_pk_fma_f32 v[250:251], v[114:115], v[114:115], v[250:251]
	v_pk_fma_f32 v[250:251], v[116:117], v[116:117], v[250:251]
	v_add_f32_e32 v140, v250, v251
	s_waitcnt vmcnt(15)
	v_lshlrev_b32_e32 v246, 16, v182
	v_and_b32_e32 v247, 0xffff0000, v182
	v_lshlrev_b32_e32 v248, 16, v183
	v_and_b32_e32 v249, 0xffff0000, v183
	v_pk_add_f32 v[110:111], v[110:111], v[246:247]
	v_pk_add_f32 v[112:113], v[112:113], v[248:249]
	v_lshlrev_b32_e32 v246, 16, v184
	v_and_b32_e32 v247, 0xffff0000, v184
	v_lshlrev_b32_e32 v248, 16, v185
	v_and_b32_e32 v249, 0xffff0000, v185
	v_pk_add_f32 v[106:107], v[106:107], v[246:247]
	v_pk_add_f32 v[108:109], v[108:109], v[248:249]
	v_cvt_pk_bf16_f32 v182, v110, v111
	v_cvt_pk_bf16_f32 v183, v112, v113
	v_cvt_pk_bf16_f32 v184, v106, v107
	v_cvt_pk_bf16_f32 v185, v108, v109
	global_store_dwordx4 v151, v[182:185], s[30:31]
	v_pk_mul_f32 v[250:251], v[110:111], v[110:111]
	v_pk_fma_f32 v[250:251], v[112:113], v[112:113], v[250:251]
	v_pk_fma_f32 v[250:251], v[106:107], v[106:107], v[250:251]
	v_pk_fma_f32 v[250:251], v[108:109], v[108:109], v[250:251]
	s_waitcnt vmcnt(15)
	v_lshlrev_b32_e32 v246, 16, v186
	v_and_b32_e32 v247, 0xffff0000, v186
	v_lshlrev_b32_e32 v248, 16, v187
	v_and_b32_e32 v249, 0xffff0000, v187
	v_pk_add_f32 v[102:103], v[102:103], v[246:247]
	v_pk_add_f32 v[104:105], v[104:105], v[248:249]
	v_lshlrev_b32_e32 v246, 16, v188
	v_and_b32_e32 v247, 0xffff0000, v188
	v_lshlrev_b32_e32 v248, 16, v189
	v_and_b32_e32 v249, 0xffff0000, v189
	v_pk_add_f32 v[98:99], v[98:99], v[246:247]
	v_pk_add_f32 v[100:101], v[100:101], v[248:249]
	v_cvt_pk_bf16_f32 v186, v102, v103
	v_cvt_pk_bf16_f32 v187, v104, v105
	v_cvt_pk_bf16_f32 v188, v98, v99
	v_cvt_pk_bf16_f32 v189, v100, v101
	global_store_dwordx4 v151, v[186:189], s[30:31] offset:64
	v_pk_fma_f32 v[250:251], v[102:103], v[102:103], v[250:251]
	v_pk_fma_f32 v[250:251], v[104:105], v[104:105], v[250:251]
	v_pk_fma_f32 v[250:251], v[98:99], v[98:99], v[250:251]
	v_pk_fma_f32 v[250:251], v[100:101], v[100:101], v[250:251]
	v_add_f32_e32 v141, v250, v251
	s_waitcnt vmcnt(15)
	v_lshlrev_b32_e32 v246, 16, v190
	v_and_b32_e32 v247, 0xffff0000, v190
	v_lshlrev_b32_e32 v248, 16, v191
	v_and_b32_e32 v249, 0xffff0000, v191
	v_pk_add_f32 v[94:95], v[94:95], v[246:247]
	v_pk_add_f32 v[96:97], v[96:97], v[248:249]
	v_lshlrev_b32_e32 v246, 16, v192
	v_and_b32_e32 v247, 0xffff0000, v192
	v_lshlrev_b32_e32 v248, 16, v193
	v_and_b32_e32 v249, 0xffff0000, v193
	v_pk_add_f32 v[90:91], v[90:91], v[246:247]
	v_pk_add_f32 v[92:93], v[92:93], v[248:249]
	v_cvt_pk_bf16_f32 v190, v94, v95
	v_cvt_pk_bf16_f32 v191, v96, v97
	v_cvt_pk_bf16_f32 v192, v90, v91
	v_cvt_pk_bf16_f32 v193, v92, v93
	global_store_dwordx4 v152, v[190:193], s[30:31]
	v_pk_mul_f32 v[250:251], v[94:95], v[94:95]
	v_pk_fma_f32 v[250:251], v[96:97], v[96:97], v[250:251]
	v_pk_fma_f32 v[250:251], v[90:91], v[90:91], v[250:251]
	v_pk_fma_f32 v[250:251], v[92:93], v[92:93], v[250:251]
	s_waitcnt vmcnt(15)
	v_lshlrev_b32_e32 v246, 16, v194
	v_and_b32_e32 v247, 0xffff0000, v194
	v_lshlrev_b32_e32 v248, 16, v195
	v_and_b32_e32 v249, 0xffff0000, v195
	v_pk_add_f32 v[86:87], v[86:87], v[246:247]
	v_pk_add_f32 v[88:89], v[88:89], v[248:249]
	v_lshlrev_b32_e32 v246, 16, v196
	v_and_b32_e32 v247, 0xffff0000, v196
	v_lshlrev_b32_e32 v248, 16, v197
	v_and_b32_e32 v249, 0xffff0000, v197
	v_pk_add_f32 v[82:83], v[82:83], v[246:247]
	v_pk_add_f32 v[84:85], v[84:85], v[248:249]
	v_cvt_pk_bf16_f32 v194, v86, v87
	v_cvt_pk_bf16_f32 v195, v88, v89
	v_cvt_pk_bf16_f32 v196, v82, v83
	v_cvt_pk_bf16_f32 v197, v84, v85
	global_store_dwordx4 v152, v[194:197], s[30:31] offset:64
	v_pk_fma_f32 v[250:251], v[86:87], v[86:87], v[250:251]
	v_pk_fma_f32 v[250:251], v[88:89], v[88:89], v[250:251]
	v_pk_fma_f32 v[250:251], v[82:83], v[82:83], v[250:251]
	v_pk_fma_f32 v[250:251], v[84:85], v[84:85], v[250:251]
	v_add_f32_e32 v142, v250, v251
	s_waitcnt vmcnt(15)
; __device__ __forceinline__ float bf_lo(unsigned w) { return __uint_as_float(w << 16); }
; __device__ __forceinline__ float bf_hi(unsigned w) { return __uint_as_float(w & 0xffff0000u); }
; __device__ __forceinline__ u32x4 pack8(f32x4 a, f32x4 b) { u32x4 w; w.x = cvt_pk_bf16(a[0], a[1]); w.y = cvt_pk_bf16(a[2], a[3]); w.z = cvt_pk_bf16(b[0], b[1]); w.w = cvt_pk_bf16(b[2], b[3]); return w; }
;     __device__ __forceinline__ void operator()(f32x4 (&acc)[2][2][4][2], const Unit& u, int wr, int wc, int fr, int fq) const {
;     ...
;                 const int row = row0 + ai * HALF + m * 16; float sq = 0.f;
; #pragma unroll
;                 for (int bj = 0; bj < 2; ++bj) {
;                     const size_t off = (size_t)row * D + col0 + bj * 32;
;                     const u32x4 xw = *(const u32x4*)(xin + off);
;                     const f32x4 v0 = acc[ai][bj][m][0] + (f32x4){bf_lo(xw.x), bf_hi(xw.x), bf_lo(xw.y), bf_hi(xw.y)}, v1 = acc[ai][bj][m][1] + (f32x4){bf_lo(xw.z), bf_hi(xw.z), bf_lo(xw.w), bf_hi(xw.w)};
;                     *(u32x4*)(xb + off) = pack8(v0, v1);
;                     sq += (v0[0] * v0[0] + v0[1] * v0[1]) + (v0[2] * v0[2] + v0[3] * v0[3]) + (v1[0] * v1[0] + v1[1] * v1[1]) + (v1[2] * v1[2] + v1[3] * v1[3]);
;                 }
	v_lshlrev_b32_e32 v246, 16, v198
	v_and_b32_e32 v247, 0xffff0000, v198
	v_lshlrev_b32_e32 v248, 16, v199
	v_and_b32_e32 v249, 0xffff0000, v199
	v_pk_add_f32 v[78:79], v[78:79], v[246:247]
	v_pk_add_f32 v[80:81], v[80:81], v[248:249]
	v_lshlrev_b32_e32 v246, 16, v200
	v_and_b32_e32 v247, 0xffff0000, v200
	v_lshlrev_b32_e32 v248, 16, v201
	v_and_b32_e32 v249, 0xffff0000, v201
	v_pk_add_f32 v[74:75], v[74:75], v[246:247]
	v_pk_add_f32 v[76:77], v[76:77], v[248:249]
	v_cvt_pk_bf16_f32 v198, v78, v79
	v_cvt_pk_bf16_f32 v199, v80, v81
	v_cvt_pk_bf16_f32 v200, v74, v75
	v_cvt_pk_bf16_f32 v201, v76, v77
	global_store_dwordx4 v153, v[198:201], s[30:31]
	v_pk_mul_f32 v[250:251], v[78:79], v[78:79]
	v_pk_fma_f32 v[250:251], v[80:81], v[80:81], v[250:251]
	v_pk_fma_f32 v[250:251], v[74:75], v[74:75], v[250:251]
	v_pk_fma_f32 v[250:251], v[76:77], v[76:77], v[250:251]
	s_waitcnt vmcnt(15)
	v_lshlrev_b32_e32 v246, 16, v202
	v_and_b32_e32 v247, 0xffff0000, v202
	v_lshlrev_b32_e32 v248, 16, v203
	v_and_b32_e32 v249, 0xffff0000, v203
	v_pk_add_f32 v[70:71], v[70:71], v[246:247]
	v_pk_add_f32 v[72:73], v[72:73], v[248:249]
	v_lshlrev_b32_e32 v246, 16, v204
	v_and_b32_e32 v247, 0xffff0000, v204
	v_lshlrev_b32_e32 v248, 16, v205
	v_and_b32_e32 v249, 0xffff0000, v205
	v_pk_add_f32 v[66:67], v[66:67], v[246:247]
	v_pk_add_f32 v[68:69], v[68:69], v[248:249]
	v_cvt_pk_bf16_f32 v202, v70, v71
	v_cvt_pk_bf16_f32 v203, v72, v73
	v_cvt_pk_bf16_f32 v204, v66, v67
	v_cvt_pk_bf16_f32 v205, v68, v69
	global_store_dwordx4 v153, v[202:205], s[30:31] offset:64
	v_pk_fma_f32 v[250:251], v[70:71], v[70:71], v[250:251]
	v_pk_fma_f32 v[250:251], v[72:73], v[72:73], v[250:251]
	v_pk_fma_f32 v[250:251], v[66:67], v[66:67], v[250:251]
	v_pk_fma_f32 v[250:251], v[68:69], v[68:69], v[250:251]
	v_add_f32_e32 v143, v250, v251
	s_waitcnt vmcnt(15)
	v_lshlrev_b32_e32 v246, 16, v206
	v_and_b32_e32 v247, 0xffff0000, v206
	v_lshlrev_b32_e32 v248, 16, v207
	v_and_b32_e32 v249, 0xffff0000, v207
	v_pk_add_f32 v[62:63], v[62:63], v[246:247]
	v_pk_add_f32 v[64:65], v[64:65], v[248:249]
	v_lshlrev_b32_e32 v246, 16, v208
	v_and_b32_e32 v247, 0xffff0000, v208
	v_lshlrev_b32_e32 v248, 16, v209
	v_and_b32_e32 v249, 0xffff0000, v209
	v_pk_add_f32 v[58:59], v[58:59], v[246:247]
	v_pk_add_f32 v[60:61], v[60:61], v[248:249]
	v_cvt_pk_bf16_f32 v206, v62, v63
	v_cvt_pk_bf16_f32 v207, v64, v65
	v_cvt_pk_bf16_f32 v208, v58, v59
	v_cvt_pk_bf16_f32 v209, v60, v61
	global_store_dwordx4 v154, v[206:209], s[30:31]
	v_pk_mul_f32 v[250:251], v[62:63], v[62:63]
	v_pk_fma_f32 v[250:251], v[64:65], v[64:65], v[250:251]
	v_pk_fma_f32 v[250:251], v[58:59], v[58:59], v[250:251]
	v_pk_fma_f32 v[250:251], v[60:61], v[60:61], v[250:251]
	s_waitcnt vmcnt(15)
	v_lshlrev_b32_e32 v246, 16, v210
	v_and_b32_e32 v247, 0xffff0000, v210
	v_lshlrev_b32_e32 v248, 16, v211
	v_and_b32_e32 v249, 0xffff0000, v211
	v_pk_add_f32 v[54:55], v[54:55], v[246:247]
	v_pk_add_f32 v[56:57], v[56:57], v[248:249]
	v_lshlrev_b32_e32 v246, 16, v212
	v_and_b32_e32 v247, 0xffff0000, v212
	v_lshlrev_b32_e32 v248, 16, v213
	v_and_b32_e32 v249, 0xffff0000, v213
	v_pk_add_f32 v[50:51], v[50:51], v[246:247]
	v_pk_add_f32 v[52:53], v[52:53], v[248:249]
	v_cvt_pk_bf16_f32 v210, v54, v55
	v_cvt_pk_bf16_f32 v211, v56, v57
	v_cvt_pk_bf16_f32 v212, v50, v51
	v_cvt_pk_bf16_f32 v213, v52, v53
	global_store_dwordx4 v154, v[210:213], s[30:31] offset:64
	v_pk_fma_f32 v[250:251], v[54:55], v[54:55], v[250:251]
	v_pk_fma_f32 v[250:251], v[56:57], v[56:57], v[250:251]
	v_pk_fma_f32 v[250:251], v[50:51], v[50:51], v[250:251]
	v_pk_fma_f32 v[250:251], v[52:53], v[52:53], v[250:251]
	v_add_f32_e32 v144, v250, v251
	s_waitcnt vmcnt(15)
	v_lshlrev_b32_e32 v246, 16, v214
	v_and_b32_e32 v247, 0xffff0000, v214
	v_lshlrev_b32_e32 v248, 16, v215
	v_and_b32_e32 v249, 0xffff0000, v215
	v_pk_add_f32 v[46:47], v[46:47], v[246:247]
	v_pk_add_f32 v[48:49], v[48:49], v[248:249]
	v_lshlrev_b32_e32 v246, 16, v216
	v_and_b32_e32 v247, 0xffff0000, v216
	v_lshlrev_b32_e32 v248, 16, v217
	v_and_b32_e32 v249, 0xffff0000, v217
	v_pk_add_f32 v[42:43], v[42:43], v[246:247]
	v_pk_add_f32 v[44:45], v[44:45], v[248:249]
	v_cvt_pk_bf16_f32 v214, v46, v47
	v_cvt_pk_bf16_f32 v215, v48, v49
	v_cvt_pk_bf16_f32 v216, v42, v43
	v_cvt_pk_bf16_f32 v217, v44, v45
	global_store_dwordx4 v155, v[214:217], s[30:31]
	v_pk_mul_f32 v[250:251], v[46:47], v[46:47]
	v_pk_fma_f32 v[250:251], v[48:49], v[48:49], v[250:251]
	v_pk_fma_f32 v[250:251], v[42:43], v[42:43], v[250:251]
	v_pk_fma_f32 v[250:251], v[44:45], v[44:45], v[250:251]
	s_waitcnt vmcnt(15)
	v_lshlrev_b32_e32 v246, 16, v218
	v_and_b32_e32 v247, 0xffff0000, v218
	v_lshlrev_b32_e32 v248, 16, v219
	v_and_b32_e32 v249, 0xffff0000, v219
	v_pk_add_f32 v[38:39], v[38:39], v[246:247]
	v_pk_add_f32 v[40:41], v[40:41], v[248:249]
	v_lshlrev_b32_e32 v246, 16, v220
	v_and_b32_e32 v247, 0xffff0000, v220
	v_lshlrev_b32_e32 v248, 16, v221
	v_and_b32_e32 v249, 0xffff0000, v221
	v_pk_add_f32 v[34:35], v[34:35], v[246:247]
	v_pk_add_f32 v[36:37], v[36:37], v[248:249]
	v_cvt_pk_bf16_f32 v218, v38, v39
	v_cvt_pk_bf16_f32 v219, v40, v41
	v_cvt_pk_bf16_f32 v220, v34, v35
	v_cvt_pk_bf16_f32 v221, v36, v37
	global_store_dwordx4 v155, v[218:221], s[30:31] offset:64
	v_pk_fma_f32 v[250:251], v[38:39], v[38:39], v[250:251]
	v_pk_fma_f32 v[250:251], v[40:41], v[40:41], v[250:251]
	v_pk_fma_f32 v[250:251], v[34:35], v[34:35], v[250:251]
	v_pk_fma_f32 v[250:251], v[36:37], v[36:37], v[250:251]
	v_add_f32_e32 v145, v250, v251
	s_waitcnt vmcnt(15)
; #define PG8_BAR __builtin_amdgcn_s_barrier()
; template <class Epi, class SchedT, bool ALIGN_EPI, bool SP2>
; __device__ __forceinline__ void gemm_phase(LAS unsigned char* lds, const int ldk, const int nt, const SchedT& S, const Epi& E) {
;     ...
;         if (!has_next) break;
;         if (!(SchedT::kMode == 2 && cur.kind == 0)) {
; #pragma unroll
;         for (int a = 0; a < 2; ++a)
; #pragma unroll
;             for (int b = 0; b < 2; ++b)
; #pragma unroll
;                 for (int m = 0; m < 4; ++m)
; #pragma unroll
;                     for (int n = 0; n < 2; ++n) acc[a][b][m][n] = (f32x4){0.f, 0.f, 0.f, 0.f};
;         }
;         cur = nxt; cA = nA; cB = nB; ++ui;
;         if constexpr (ALIGN_EPI) { if (wr == 1) PG8_BAR; }
;     __device__ __forceinline__ void operator()(f32x4 (&acc)[2][2][4][2], const Unit& u, int wr, int wc, int fr, int fq) const {
;     ...
;                     sq += (v0[0] * v0[0] + v0[1] * v0[1]) + (v0[2] * v0[2] + v0[3] * v0[3]) + (v1[0] * v1[0] + v1[1] * v1[1]) + (v1[2] * v1[2] + v1[3] * v1[3]);
;                 }
;                 sq += __shfl_xor(sq, 16); sq += __shfl_xor(sq, 32);
;                 if (fq == 0) ss[(size_t)row * 32 + u.pn * 4 + wc] = sq;
;             }
	v_lshlrev_b32_e32 v246, 16, v222
	v_and_b32_e32 v247, 0xffff0000, v222
	v_lshlrev_b32_e32 v248, 16, v223
	v_and_b32_e32 v249, 0xffff0000, v223
	v_pk_add_f32 v[30:31], v[30:31], v[246:247]
	v_pk_add_f32 v[32:33], v[32:33], v[248:249]
	v_lshlrev_b32_e32 v246, 16, v224
	v_and_b32_e32 v247, 0xffff0000, v224
	v_lshlrev_b32_e32 v248, 16, v225
	v_and_b32_e32 v249, 0xffff0000, v225
	v_pk_add_f32 v[26:27], v[26:27], v[246:247]
	v_pk_add_f32 v[28:29], v[28:29], v[248:249]
	v_cvt_pk_bf16_f32 v222, v30, v31
	v_cvt_pk_bf16_f32 v223, v32, v33
	v_cvt_pk_bf16_f32 v224, v26, v27
	v_cvt_pk_bf16_f32 v225, v28, v29
	global_store_dwordx4 v156, v[222:225], s[30:31]
	v_pk_mul_f32 v[250:251], v[30:31], v[30:31]
	v_pk_fma_f32 v[250:251], v[32:33], v[32:33], v[250:251]
	v_pk_fma_f32 v[250:251], v[26:27], v[26:27], v[250:251]
	v_pk_fma_f32 v[250:251], v[28:29], v[28:29], v[250:251]
	s_waitcnt vmcnt(15)
	v_lshlrev_b32_e32 v246, 16, v226
	v_and_b32_e32 v247, 0xffff0000, v226
	v_lshlrev_b32_e32 v248, 16, v227
	v_and_b32_e32 v249, 0xffff0000, v227
	v_pk_add_f32 v[22:23], v[22:23], v[246:247]
	v_pk_add_f32 v[24:25], v[24:25], v[248:249]
	v_lshlrev_b32_e32 v246, 16, v228
	v_and_b32_e32 v247, 0xffff0000, v228
	v_lshlrev_b32_e32 v248, 16, v229
	v_and_b32_e32 v249, 0xffff0000, v229
	v_pk_add_f32 v[18:19], v[18:19], v[246:247]
	v_pk_add_f32 v[20:21], v[20:21], v[248:249]
	v_cvt_pk_bf16_f32 v226, v22, v23
	v_cvt_pk_bf16_f32 v227, v24, v25
	v_cvt_pk_bf16_f32 v228, v18, v19
	v_cvt_pk_bf16_f32 v229, v20, v21
	global_store_dwordx4 v156, v[226:229], s[30:31] offset:64
	v_pk_fma_f32 v[250:251], v[22:23], v[22:23], v[250:251]
	v_pk_fma_f32 v[250:251], v[24:25], v[24:25], v[250:251]
	v_pk_fma_f32 v[250:251], v[18:19], v[18:19], v[250:251]
	v_pk_fma_f32 v[250:251], v[20:21], v[20:21], v[250:251]
	v_add_f32_e32 v162, v250, v251
	s_waitcnt vmcnt(15)
	v_lshlrev_b32_e32 v246, 16, v230
	v_and_b32_e32 v247, 0xffff0000, v230
	v_lshlrev_b32_e32 v248, 16, v231
	v_and_b32_e32 v249, 0xffff0000, v231
	v_pk_add_f32 v[14:15], v[14:15], v[246:247]
	v_pk_add_f32 v[16:17], v[16:17], v[248:249]
	v_lshlrev_b32_e32 v246, 16, v232
	v_and_b32_e32 v247, 0xffff0000, v232
	v_lshlrev_b32_e32 v248, 16, v233
	v_and_b32_e32 v249, 0xffff0000, v233
	v_pk_add_f32 v[10:11], v[10:11], v[246:247]
	v_pk_add_f32 v[12:13], v[12:13], v[248:249]
	v_cvt_pk_bf16_f32 v230, v14, v15
	v_cvt_pk_bf16_f32 v231, v16, v17
	v_cvt_pk_bf16_f32 v232, v10, v11
	v_cvt_pk_bf16_f32 v233, v12, v13
	global_store_dwordx4 v157, v[230:233], s[30:31]
	v_pk_mul_f32 v[250:251], v[14:15], v[14:15]
	v_pk_fma_f32 v[250:251], v[16:17], v[16:17], v[250:251]
	v_pk_fma_f32 v[250:251], v[10:11], v[10:11], v[250:251]
	v_pk_fma_f32 v[250:251], v[12:13], v[12:13], v[250:251]
	s_waitcnt vmcnt(15)
	v_lshlrev_b32_e32 v246, 16, v234
	v_and_b32_e32 v247, 0xffff0000, v234
	v_lshlrev_b32_e32 v248, 16, v235
	v_and_b32_e32 v249, 0xffff0000, v235
	v_pk_add_f32 v[6:7], v[6:7], v[246:247]
	v_pk_add_f32 v[8:9], v[8:9], v[248:249]
	v_lshlrev_b32_e32 v246, 16, v236
	v_and_b32_e32 v247, 0xffff0000, v236
	v_lshlrev_b32_e32 v248, 16, v237
	v_and_b32_e32 v249, 0xffff0000, v237
	v_pk_add_f32 v[2:3], v[2:3], v[246:247]
	v_pk_add_f32 v[4:5], v[4:5], v[248:249]
	v_cvt_pk_bf16_f32 v234, v6, v7
	v_cvt_pk_bf16_f32 v235, v8, v9
	v_cvt_pk_bf16_f32 v236, v2, v3
	v_cvt_pk_bf16_f32 v237, v4, v5
	global_store_dwordx4 v157, v[234:237], s[30:31] offset:64
	v_pk_fma_f32 v[250:251], v[6:7], v[6:7], v[250:251]
	v_pk_fma_f32 v[250:251], v[8:9], v[8:9], v[250:251]
	v_pk_fma_f32 v[250:251], v[2:3], v[2:3], v[250:251]
	v_pk_fma_f32 v[250:251], v[4:5], v[4:5], v[250:251]
	v_add_f32_e32 v238, v250, v251
	ds_bpermute_b32 v174, v239, v140
	ds_bpermute_b32 v175, v239, v141
	ds_bpermute_b32 v176, v239, v142
	ds_bpermute_b32 v177, v239, v143
	ds_bpermute_b32 v178, v239, v144
	ds_bpermute_b32 v179, v239, v145
	ds_bpermute_b32 v180, v239, v162
	ds_bpermute_b32 v181, v239, v238
	s_waitcnt lgkmcnt(0)
	v_add_f32_e32 v140, v140, v174
	v_add_f32_e32 v141, v141, v175
	v_add_f32_e32 v142, v142, v176
	v_add_f32_e32 v143, v143, v177
	v_add_f32_e32 v144, v144, v178
	v_add_f32_e32 v145, v145, v179
	v_add_f32_e32 v162, v162, v180
	v_add_f32_e32 v238, v238, v181
	ds_bpermute_b32 v174, v252, v140
	ds_bpermute_b32 v175, v252, v141
	ds_bpermute_b32 v176, v252, v142
	ds_bpermute_b32 v177, v252, v143
	ds_bpermute_b32 v178, v252, v144
	ds_bpermute_b32 v179, v252, v145
	ds_bpermute_b32 v180, v252, v162
	ds_bpermute_b32 v181, v252, v238
	s_waitcnt lgkmcnt(0)
	v_add_f32_e32 v140, v140, v174
	v_add_f32_e32 v141, v141, v175
	v_add_f32_e32 v142, v142, v176
	v_add_f32_e32 v143, v143, v177
	v_add_f32_e32 v144, v144, v178
	v_add_f32_e32 v145, v145, v179
	v_add_f32_e32 v162, v162, v180
	v_add_f32_e32 v238, v238, v181
	s_and_saveexec_b64 s[12:13], s[36:37]
	global_store_dword v158, v140, s[34:35]
	global_store_dword v158, v141, s[34:35] offset:2048
	global_store_dword v159, v142, s[34:35]
	global_store_dword v159, v143, s[34:35] offset:2048
	global_store_dword v160, v144, s[34:35]
	global_store_dword v160, v145, s[34:35] offset:2048
	global_store_dword v161, v162, s[34:35]
	global_store_dword v161, v238, s[34:35] offset:2048
	s_mov_b32 s65, 0x10000
	s_or_b64 exec, exec, s[12:13]
	s_and_b64 vcc, exec, s[38:39]
	s_mov_b64 s[12:13], -1
	s_cbranch_vccnz .LBB0_942
	s_setprio 2
	s_andn2_b64 vcc, exec, s[18:19]
	s_cbranch_vccnz .LBB0_941
	s_barrier
	s_setprio 3
	s_branch .LBB0_941
